# SG unit: row LayerNorm loop batched over 16 rows (16 loads in flight, butterfly reductions across rows per LDS round trip)
# baseline (speedup 1.0000x reference)
; __device__ __forceinline__ void sg_unit(const Params& P, int l, int chunk, char* shm, float* ssb) {
;     ...
;     const int R0 = chunk * 128;
;     bf16_t* vt = (bf16_t*)(shm + SG_VT);
;     const float* gs = P.g_sgu + l * 256;
;     const f32x4 g4 = *(const f32x4*)(gs + 4 * lane);
;     for (int q = wid * 16; q < wid * 16 + 16; ++q) {
;         const u32x2 vv = *(const u32x2*)(qkv + (size_t)(R0 + q) * DIN + C_V + 4 * lane);
;         f32x4 v; v[0] = __uint_as_float(vv.x << 16); v[1] = __uint_as_float(vv.x & 0xffff0000u); v[2] = __uint_as_float(vv.y << 16); v[3] = __uint_as_float(vv.y & 0xffff0000u);
;         const float mean = wave_sum((v[0] + v[1]) + (v[2] + v[3])) * (1.f / 256.f);
;         v = v - mean; const f32x4 sq = v * v;
;         const float rstd = 1.f / sqrtf(wave_sum((sq[0] + sq[1]) + (sq[2] + sq[3])) * (1.f / 256.f) + LN_EPS);
;         v = v * rstd * g4;
.LBB0_556:
	s_andn2_b64 vcc, exec, s[0:1]
	s_cbranch_vccnz .LBB0_579
	s_add_i32 s3, s48, 0xfffffd00
	s_add_i32 s0, s48, 0xfffffcbe
	s_cmpk_lt_u32 s3, 0x42
	s_cselect_b32 s0, s3, s0
	s_cmp_lt_u32 s0, 64
	v_readlane_b32 s4, v252, 11
	s_cselect_b64 s[0:1], -1, 0
	v_readlane_b32 s5, v252, 12
	s_or_b64 s[0:1], s[4:5], s[0:1]
	s_andn2_b64 vcc, exec, s[0:1]
	s_cbranch_vccnz .LBB0_579
	s_mov_b64 s[4:5], s[76:77]
	v_mov_b32 v12, v214
	v_readlane_b32 s0, v252, 18
	v_and_b32_e32 v13, 63, v12
	v_lshlrev_b32_e32 v0, 4, v13
	v_readlane_b32 s1, v252, 19
	v_xor_b32_e32 v6, 1, v220
	v_readfirstlane_b32 s6, v12
	s_ashr_i32 s2, s6, 6
	v_readlane_b32 s8, v254, 36
	s_mov_b32 s7, 0
	global_load_dwordx4 v[2:5], v0, s[0:1]
	v_and_b32_e32 v0, 64, v220
	v_add_u32_e32 v0, 64, v0
	v_cmp_lt_i32_e32 vcc, v6, v0
	s_lshl_b32 s1, s2, 5
	s_add_i32 s1, s1, 0
	v_cndmask_b32_e32 v6, v220, v6, vcc
	v_lshlrev_b32_e32 v17, 2, v6
	v_xor_b32_e32 v6, 2, v220
	v_cmp_lt_i32_e32 vcc, v6, v0
	s_lshl_b32 s0, s2, 4
	s_nop 0
	v_cndmask_b32_e32 v6, v220, v6, vcc
	v_lshlrev_b32_e32 v83, 2, v6
	v_xor_b32_e32 v6, 4, v220
	v_cmp_lt_i32_e32 vcc, v6, v0
	s_nop 1
	v_cndmask_b32_e32 v6, v220, v6, vcc
	v_lshlrev_b32_e32 v82, 2, v6
	v_xor_b32_e32 v6, 8, v220
	v_cmp_lt_i32_e32 vcc, v6, v0
	s_nop 1
	v_cndmask_b32_e32 v6, v220, v6, vcc
	v_lshlrev_b32_e32 v14, 2, v6
	v_xor_b32_e32 v6, 16, v220
	v_cmp_lt_i32_e32 vcc, v6, v0
	s_nop 1
	v_cndmask_b32_e32 v6, v220, v6, vcc
	v_lshlrev_b32_e32 v15, 2, v6
	v_xor_b32_e32 v6, 32, v220
	v_cmp_lt_i32_e32 vcc, v6, v0
	s_nop 1
	v_cndmask_b32_e32 v0, v220, v6, vcc
	v_lshlrev_b32_e32 v18, 2, v0
	v_mov_b32_e32 v0, s1
	s_movk_i32 s1, 0x440
	v_mad_u32_u24 v19, v13, s1, v0
	s_lshl_b32 s1, s48, 7
	s_add_i32 s0, s1, s0
	s_add_i32 s0, s0, 0xfffe8000
	s_mul_hi_i32 s1, s0, 0x1200
	s_mulk_i32 s0, 0x1200
	s_add_u32 s0, s8, s0
	v_readlane_b32 s8, v254, 37
	v_lshlrev_b32_e32 v0, 3, v13
	s_addc_u32 s1, s8, s1
	v_lshl_add_u64 v[6:7], s[0:1], 0, v[0:1]
	s_mov_b64 s[8:9], 0x1200
	global_load_dwordx2 v[96:97], v[6:7], off
	v_lshl_add_u64 v[6:7], v[6:7], 0, s[8:9]
	global_load_dwordx2 v[98:99], v[6:7], off
	v_lshl_add_u64 v[6:7], v[6:7], 0, s[8:9]
	global_load_dwordx2 v[100:101], v[6:7], off
	v_lshl_add_u64 v[6:7], v[6:7], 0, s[8:9]
	global_load_dwordx2 v[102:103], v[6:7], off
	v_lshl_add_u64 v[6:7], v[6:7], 0, s[8:9]
	global_load_dwordx2 v[104:105], v[6:7], off
	v_lshl_add_u64 v[6:7], v[6:7], 0, s[8:9]
	global_load_dwordx2 v[106:107], v[6:7], off
	v_lshl_add_u64 v[6:7], v[6:7], 0, s[8:9]
	global_load_dwordx2 v[108:109], v[6:7], off
	v_lshl_add_u64 v[6:7], v[6:7], 0, s[8:9]
	global_load_dwordx2 v[110:111], v[6:7], off
	v_lshl_add_u64 v[6:7], v[6:7], 0, s[8:9]
	global_load_dwordx2 v[112:113], v[6:7], off
	v_lshl_add_u64 v[6:7], v[6:7], 0, s[8:9]
	global_load_dwordx2 v[114:115], v[6:7], off
	v_lshl_add_u64 v[6:7], v[6:7], 0, s[8:9]
	global_load_dwordx2 v[116:117], v[6:7], off
	v_lshl_add_u64 v[6:7], v[6:7], 0, s[8:9]
	global_load_dwordx2 v[118:119], v[6:7], off
	v_lshl_add_u64 v[6:7], v[6:7], 0, s[8:9]
	global_load_dwordx2 v[120:121], v[6:7], off
	v_lshl_add_u64 v[6:7], v[6:7], 0, s[8:9]
	global_load_dwordx2 v[122:123], v[6:7], off
	v_lshl_add_u64 v[6:7], v[6:7], 0, s[8:9]
	global_load_dwordx2 v[124:125], v[6:7], off
	v_lshl_add_u64 v[6:7], v[6:7], 0, s[8:9]
	global_load_dwordx2 v[126:127], v[6:7], off
	s_waitcnt vmcnt(0)
	v_lshlrev_b32_e32 v130, 16, v97
	v_lshlrev_b32_e32 v128, 16, v96
	v_and_b32_e32 v131, 0xffff0000, v97
	v_and_b32_e32 v129, 0xffff0000, v96
	v_lshlrev_b32_e32 v134, 16, v99
	v_lshlrev_b32_e32 v132, 16, v98
	v_and_b32_e32 v135, 0xffff0000, v99
	v_and_b32_e32 v133, 0xffff0000, v98
	v_lshlrev_b32_e32 v138, 16, v101
	v_lshlrev_b32_e32 v136, 16, v100
	v_and_b32_e32 v139, 0xffff0000, v101
	v_and_b32_e32 v137, 0xffff0000, v100
	v_lshlrev_b32_e32 v142, 16, v103
	v_lshlrev_b32_e32 v140, 16, v102
	v_and_b32_e32 v143, 0xffff0000, v103
	v_and_b32_e32 v141, 0xffff0000, v102
	v_lshlrev_b32_e32 v146, 16, v105
	v_lshlrev_b32_e32 v144, 16, v104
	v_and_b32_e32 v147, 0xffff0000, v105
	v_and_b32_e32 v145, 0xffff0000, v104
	v_lshlrev_b32_e32 v150, 16, v107
	v_lshlrev_b32_e32 v148, 16, v106
	v_and_b32_e32 v151, 0xffff0000, v107
	v_and_b32_e32 v149, 0xffff0000, v106
	v_lshlrev_b32_e32 v154, 16, v109
	v_lshlrev_b32_e32 v152, 16, v108
	v_and_b32_e32 v155, 0xffff0000, v109
	v_and_b32_e32 v153, 0xffff0000, v108
	v_lshlrev_b32_e32 v158, 16, v111
	v_lshlrev_b32_e32 v156, 16, v110
	v_and_b32_e32 v159, 0xffff0000, v111
	v_and_b32_e32 v157, 0xffff0000, v110
	v_lshlrev_b32_e32 v162, 16, v113
	v_lshlrev_b32_e32 v160, 16, v112
	v_and_b32_e32 v163, 0xffff0000, v113
	v_and_b32_e32 v161, 0xffff0000, v112
	v_lshlrev_b32_e32 v166, 16, v115
	v_lshlrev_b32_e32 v164, 16, v114
	v_and_b32_e32 v167, 0xffff0000, v115
	v_and_b32_e32 v165, 0xffff0000, v114
	v_lshlrev_b32_e32 v170, 16, v117
	v_lshlrev_b32_e32 v168, 16, v116
	v_and_b32_e32 v171, 0xffff0000, v117
	v_and_b32_e32 v169, 0xffff0000, v116
	v_lshlrev_b32_e32 v174, 16, v119
	v_lshlrev_b32_e32 v172, 16, v118
	v_and_b32_e32 v175, 0xffff0000, v119
	v_and_b32_e32 v173, 0xffff0000, v118
	v_lshlrev_b32_e32 v178, 16, v121
	v_lshlrev_b32_e32 v176, 16, v120
	v_and_b32_e32 v179, 0xffff0000, v121
	v_and_b32_e32 v177, 0xffff0000, v120
	v_lshlrev_b32_e32 v182, 16, v123
	v_lshlrev_b32_e32 v180, 16, v122
	v_and_b32_e32 v183, 0xffff0000, v123
	v_and_b32_e32 v181, 0xffff0000, v122
	v_lshlrev_b32_e32 v186, 16, v125
	v_lshlrev_b32_e32 v184, 16, v124
	v_and_b32_e32 v187, 0xffff0000, v125
	v_and_b32_e32 v185, 0xffff0000, v124
	v_lshlrev_b32_e32 v190, 16, v127
	v_lshlrev_b32_e32 v188, 16, v126
	v_and_b32_e32 v191, 0xffff0000, v127
	v_and_b32_e32 v189, 0xffff0000, v126
; __device__ __forceinline__ float wave_sum(float v) {
; #pragma unroll
;     for (int o = 1; o < 64; o <<= 1) v += __shfl_xor(v, o);
;     return v;
; __device__ __forceinline__ void sg_unit(const Params& P, int l, int chunk, char* shm, float* ssb) {
;     ...
;     for (int q = wid * 16; q < wid * 16 + 16; ++q) {
;         const u32x2 vv = *(const u32x2*)(qkv + (size_t)(R0 + q) * DIN + C_V + 4 * lane);
;         f32x4 v; v[0] = __uint_as_float(vv.x << 16); v[1] = __uint_as_float(vv.x & 0xffff0000u); v[2] = __uint_as_float(vv.y << 16); v[3] = __uint_as_float(vv.y & 0xffff0000u);
;         const float mean = wave_sum((v[0] + v[1]) + (v[2] + v[3])) * (1.f / 256.f);
;         v = v - mean; const f32x4 sq = v * v;
;         const float rstd = 1.f / sqrtf(wave_sum((sq[0] + sq[1]) + (sq[2] + sq[3])) * (1.f / 256.f) + LN_EPS);
	v_add_f32_e32 v208, v128, v129
	v_add_f32_e32 v209, v130, v131
	v_add_f32_e32 v192, v208, v209
	v_add_f32_e32 v208, v132, v133
	v_add_f32_e32 v209, v134, v135
	v_add_f32_e32 v193, v208, v209
	v_add_f32_e32 v208, v136, v137
	v_add_f32_e32 v209, v138, v139
	v_add_f32_e32 v194, v208, v209
	v_add_f32_e32 v208, v140, v141
	v_add_f32_e32 v209, v142, v143
	v_add_f32_e32 v195, v208, v209
	v_add_f32_e32 v208, v144, v145
	v_add_f32_e32 v209, v146, v147
	v_add_f32_e32 v196, v208, v209
	v_add_f32_e32 v208, v148, v149
	v_add_f32_e32 v209, v150, v151
	v_add_f32_e32 v197, v208, v209
	v_add_f32_e32 v208, v152, v153
	v_add_f32_e32 v209, v154, v155
	v_add_f32_e32 v198, v208, v209
	v_add_f32_e32 v208, v156, v157
	v_add_f32_e32 v209, v158, v159
	v_add_f32_e32 v199, v208, v209
	v_add_f32_e32 v208, v160, v161
	v_add_f32_e32 v209, v162, v163
	v_add_f32_e32 v200, v208, v209
	v_add_f32_e32 v208, v164, v165
	v_add_f32_e32 v209, v166, v167
	v_add_f32_e32 v201, v208, v209
	v_add_f32_e32 v208, v168, v169
	v_add_f32_e32 v209, v170, v171
	v_add_f32_e32 v202, v208, v209
	v_add_f32_e32 v208, v172, v173
	v_add_f32_e32 v209, v174, v175
	v_add_f32_e32 v203, v208, v209
	v_add_f32_e32 v208, v176, v177
	v_add_f32_e32 v209, v178, v179
	v_add_f32_e32 v204, v208, v209
	v_add_f32_e32 v208, v180, v181
	v_add_f32_e32 v209, v182, v183
	v_add_f32_e32 v205, v208, v209
	v_add_f32_e32 v208, v184, v185
	v_add_f32_e32 v209, v186, v187
	v_add_f32_e32 v206, v208, v209
	v_add_f32_e32 v208, v188, v189
	v_add_f32_e32 v209, v190, v191
	v_add_f32_e32 v207, v208, v209
	ds_bpermute_b32 v96, v17, v192
	ds_bpermute_b32 v97, v17, v193
	ds_bpermute_b32 v98, v17, v194
	ds_bpermute_b32 v99, v17, v195
	ds_bpermute_b32 v100, v17, v196
	ds_bpermute_b32 v101, v17, v197
	ds_bpermute_b32 v102, v17, v198
	ds_bpermute_b32 v103, v17, v199
	ds_bpermute_b32 v104, v17, v200
	ds_bpermute_b32 v105, v17, v201
	ds_bpermute_b32 v106, v17, v202
	ds_bpermute_b32 v107, v17, v203
	ds_bpermute_b32 v108, v17, v204
	ds_bpermute_b32 v109, v17, v205
	ds_bpermute_b32 v110, v17, v206
	ds_bpermute_b32 v111, v17, v207
	s_waitcnt lgkmcnt(8)
	v_add_f32_e32 v192, v192, v96
	v_add_f32_e32 v193, v193, v97
	v_add_f32_e32 v194, v194, v98
	v_add_f32_e32 v195, v195, v99
	v_add_f32_e32 v196, v196, v100
	v_add_f32_e32 v197, v197, v101
	v_add_f32_e32 v198, v198, v102
	v_add_f32_e32 v199, v199, v103
	s_waitcnt lgkmcnt(0)
	v_add_f32_e32 v200, v200, v104
	v_add_f32_e32 v201, v201, v105
	v_add_f32_e32 v202, v202, v106
	v_add_f32_e32 v203, v203, v107
	v_add_f32_e32 v204, v204, v108
	v_add_f32_e32 v205, v205, v109
	v_add_f32_e32 v206, v206, v110
	v_add_f32_e32 v207, v207, v111
	ds_bpermute_b32 v96, v83, v192
	ds_bpermute_b32 v97, v83, v193
	ds_bpermute_b32 v98, v83, v194
	ds_bpermute_b32 v99, v83, v195
	ds_bpermute_b32 v100, v83, v196
	ds_bpermute_b32 v101, v83, v197
	ds_bpermute_b32 v102, v83, v198
	ds_bpermute_b32 v103, v83, v199
	ds_bpermute_b32 v104, v83, v200
	ds_bpermute_b32 v105, v83, v201
	ds_bpermute_b32 v106, v83, v202
	ds_bpermute_b32 v107, v83, v203
	ds_bpermute_b32 v108, v83, v204
	ds_bpermute_b32 v109, v83, v205
	ds_bpermute_b32 v110, v83, v206
	ds_bpermute_b32 v111, v83, v207
	s_waitcnt lgkmcnt(8)
	v_add_f32_e32 v192, v192, v96
	v_add_f32_e32 v193, v193, v97
	v_add_f32_e32 v194, v194, v98
	v_add_f32_e32 v195, v195, v99
	v_add_f32_e32 v196, v196, v100
	v_add_f32_e32 v197, v197, v101
	v_add_f32_e32 v198, v198, v102
	v_add_f32_e32 v199, v199, v103
	s_waitcnt lgkmcnt(0)
	v_add_f32_e32 v200, v200, v104
	v_add_f32_e32 v201, v201, v105
	v_add_f32_e32 v202, v202, v106
	v_add_f32_e32 v203, v203, v107
	v_add_f32_e32 v204, v204, v108
	v_add_f32_e32 v205, v205, v109
	v_add_f32_e32 v206, v206, v110
	v_add_f32_e32 v207, v207, v111
	ds_bpermute_b32 v96, v82, v192
	ds_bpermute_b32 v97, v82, v193
	ds_bpermute_b32 v98, v82, v194
	ds_bpermute_b32 v99, v82, v195
	ds_bpermute_b32 v100, v82, v196
	ds_bpermute_b32 v101, v82, v197
	ds_bpermute_b32 v102, v82, v198
	ds_bpermute_b32 v103, v82, v199
	ds_bpermute_b32 v104, v82, v200
	ds_bpermute_b32 v105, v82, v201
	ds_bpermute_b32 v106, v82, v202
	ds_bpermute_b32 v107, v82, v203
	ds_bpermute_b32 v108, v82, v204
	ds_bpermute_b32 v109, v82, v205
	ds_bpermute_b32 v110, v82, v206
	ds_bpermute_b32 v111, v82, v207
	s_waitcnt lgkmcnt(8)
	v_add_f32_e32 v192, v192, v96
	v_add_f32_e32 v193, v193, v97
	v_add_f32_e32 v194, v194, v98
	v_add_f32_e32 v195, v195, v99
	v_add_f32_e32 v196, v196, v100
	v_add_f32_e32 v197, v197, v101
	v_add_f32_e32 v198, v198, v102
	v_add_f32_e32 v199, v199, v103
	s_waitcnt lgkmcnt(0)
	v_add_f32_e32 v200, v200, v104
	v_add_f32_e32 v201, v201, v105
	v_add_f32_e32 v202, v202, v106
	v_add_f32_e32 v203, v203, v107
	v_add_f32_e32 v204, v204, v108
	v_add_f32_e32 v205, v205, v109
	v_add_f32_e32 v206, v206, v110
	v_add_f32_e32 v207, v207, v111
	ds_bpermute_b32 v96, v14, v192
	ds_bpermute_b32 v97, v14, v193
	ds_bpermute_b32 v98, v14, v194
	ds_bpermute_b32 v99, v14, v195
	ds_bpermute_b32 v100, v14, v196
	ds_bpermute_b32 v101, v14, v197
	ds_bpermute_b32 v102, v14, v198
	ds_bpermute_b32 v103, v14, v199
	ds_bpermute_b32 v104, v14, v200
	ds_bpermute_b32 v105, v14, v201
	ds_bpermute_b32 v106, v14, v202
	ds_bpermute_b32 v107, v14, v203
	ds_bpermute_b32 v108, v14, v204
	ds_bpermute_b32 v109, v14, v205
	ds_bpermute_b32 v110, v14, v206
	ds_bpermute_b32 v111, v14, v207
	s_waitcnt lgkmcnt(8)
	v_add_f32_e32 v192, v192, v96
	v_add_f32_e32 v193, v193, v97
	v_add_f32_e32 v194, v194, v98
	v_add_f32_e32 v195, v195, v99
	v_add_f32_e32 v196, v196, v100
	v_add_f32_e32 v197, v197, v101
	v_add_f32_e32 v198, v198, v102
	v_add_f32_e32 v199, v199, v103
	s_waitcnt lgkmcnt(0)
; __device__ __forceinline__ void sg_unit(const Params& P, int l, int chunk, char* shm, float* ssb) {
;     ...
;         const float mean = wave_sum((v[0] + v[1]) + (v[2] + v[3])) * (1.f / 256.f);
;         v = v - mean; const f32x4 sq = v * v;
;         const float rstd = 1.f / sqrtf(wave_sum((sq[0] + sq[1]) + (sq[2] + sq[3])) * (1.f / 256.f) + LN_EPS);
	v_add_f32_e32 v200, v200, v104
	v_add_f32_e32 v201, v201, v105
	v_add_f32_e32 v202, v202, v106
	v_add_f32_e32 v203, v203, v107
	v_add_f32_e32 v204, v204, v108
	v_add_f32_e32 v205, v205, v109
	v_add_f32_e32 v206, v206, v110
	v_add_f32_e32 v207, v207, v111
	ds_bpermute_b32 v96, v15, v192
	ds_bpermute_b32 v97, v15, v193
	ds_bpermute_b32 v98, v15, v194
	ds_bpermute_b32 v99, v15, v195
	ds_bpermute_b32 v100, v15, v196
	ds_bpermute_b32 v101, v15, v197
	ds_bpermute_b32 v102, v15, v198
	ds_bpermute_b32 v103, v15, v199
	ds_bpermute_b32 v104, v15, v200
	ds_bpermute_b32 v105, v15, v201
	ds_bpermute_b32 v106, v15, v202
	ds_bpermute_b32 v107, v15, v203
	ds_bpermute_b32 v108, v15, v204
	ds_bpermute_b32 v109, v15, v205
	ds_bpermute_b32 v110, v15, v206
	ds_bpermute_b32 v111, v15, v207
	s_waitcnt lgkmcnt(8)
	v_add_f32_e32 v192, v192, v96
	v_add_f32_e32 v193, v193, v97
	v_add_f32_e32 v194, v194, v98
	v_add_f32_e32 v195, v195, v99
	v_add_f32_e32 v196, v196, v100
	v_add_f32_e32 v197, v197, v101
	v_add_f32_e32 v198, v198, v102
	v_add_f32_e32 v199, v199, v103
	s_waitcnt lgkmcnt(0)
	v_add_f32_e32 v200, v200, v104
	v_add_f32_e32 v201, v201, v105
	v_add_f32_e32 v202, v202, v106
	v_add_f32_e32 v203, v203, v107
	v_add_f32_e32 v204, v204, v108
	v_add_f32_e32 v205, v205, v109
	v_add_f32_e32 v206, v206, v110
	v_add_f32_e32 v207, v207, v111
	ds_bpermute_b32 v96, v18, v192
	ds_bpermute_b32 v97, v18, v193
	ds_bpermute_b32 v98, v18, v194
	ds_bpermute_b32 v99, v18, v195
	ds_bpermute_b32 v100, v18, v196
	ds_bpermute_b32 v101, v18, v197
	ds_bpermute_b32 v102, v18, v198
	ds_bpermute_b32 v103, v18, v199
	ds_bpermute_b32 v104, v18, v200
	ds_bpermute_b32 v105, v18, v201
	ds_bpermute_b32 v106, v18, v202
	ds_bpermute_b32 v107, v18, v203
	ds_bpermute_b32 v108, v18, v204
	ds_bpermute_b32 v109, v18, v205
	ds_bpermute_b32 v110, v18, v206
	ds_bpermute_b32 v111, v18, v207
	s_waitcnt lgkmcnt(8)
	v_add_f32_e32 v192, v192, v96
	v_add_f32_e32 v193, v193, v97
	v_add_f32_e32 v194, v194, v98
	v_add_f32_e32 v195, v195, v99
	v_add_f32_e32 v196, v196, v100
	v_add_f32_e32 v197, v197, v101
	v_add_f32_e32 v198, v198, v102
	v_add_f32_e32 v199, v199, v103
	s_waitcnt lgkmcnt(0)
	v_add_f32_e32 v200, v200, v104
	v_add_f32_e32 v201, v201, v105
	v_add_f32_e32 v202, v202, v106
	v_add_f32_e32 v203, v203, v107
	v_add_f32_e32 v204, v204, v108
	v_add_f32_e32 v205, v205, v109
	v_add_f32_e32 v206, v206, v110
	v_add_f32_e32 v207, v207, v111
	v_fmac_f32_e32 v129, 0xbb800000, v192
	v_fmac_f32_e32 v131, 0xbb800000, v192
	v_fmac_f32_e32 v130, 0xbb800000, v192
	v_fmac_f32_e32 v128, 0xbb800000, v192
	v_fmac_f32_e32 v133, 0xbb800000, v193
	v_fmac_f32_e32 v135, 0xbb800000, v193
	v_fmac_f32_e32 v134, 0xbb800000, v193
	v_fmac_f32_e32 v132, 0xbb800000, v193
	v_fmac_f32_e32 v137, 0xbb800000, v194
	v_fmac_f32_e32 v139, 0xbb800000, v194
	v_fmac_f32_e32 v138, 0xbb800000, v194
	v_fmac_f32_e32 v136, 0xbb800000, v194
	v_fmac_f32_e32 v141, 0xbb800000, v195
	v_fmac_f32_e32 v143, 0xbb800000, v195
	v_fmac_f32_e32 v142, 0xbb800000, v195
	v_fmac_f32_e32 v140, 0xbb800000, v195
	v_fmac_f32_e32 v145, 0xbb800000, v196
	v_fmac_f32_e32 v147, 0xbb800000, v196
	v_fmac_f32_e32 v146, 0xbb800000, v196
	v_fmac_f32_e32 v144, 0xbb800000, v196
	v_fmac_f32_e32 v149, 0xbb800000, v197
	v_fmac_f32_e32 v151, 0xbb800000, v197
	v_fmac_f32_e32 v150, 0xbb800000, v197
	v_fmac_f32_e32 v148, 0xbb800000, v197
	v_fmac_f32_e32 v153, 0xbb800000, v198
	v_fmac_f32_e32 v155, 0xbb800000, v198
	v_fmac_f32_e32 v154, 0xbb800000, v198
	v_fmac_f32_e32 v152, 0xbb800000, v198
	v_fmac_f32_e32 v157, 0xbb800000, v199
	v_fmac_f32_e32 v159, 0xbb800000, v199
	v_fmac_f32_e32 v158, 0xbb800000, v199
	v_fmac_f32_e32 v156, 0xbb800000, v199
	v_fmac_f32_e32 v161, 0xbb800000, v200
	v_fmac_f32_e32 v163, 0xbb800000, v200
	v_fmac_f32_e32 v162, 0xbb800000, v200
	v_fmac_f32_e32 v160, 0xbb800000, v200
	v_fmac_f32_e32 v165, 0xbb800000, v201
	v_fmac_f32_e32 v167, 0xbb800000, v201
	v_fmac_f32_e32 v166, 0xbb800000, v201
	v_fmac_f32_e32 v164, 0xbb800000, v201
	v_fmac_f32_e32 v169, 0xbb800000, v202
	v_fmac_f32_e32 v171, 0xbb800000, v202
	v_fmac_f32_e32 v170, 0xbb800000, v202
	v_fmac_f32_e32 v168, 0xbb800000, v202
	v_fmac_f32_e32 v173, 0xbb800000, v203
	v_fmac_f32_e32 v175, 0xbb800000, v203
	v_fmac_f32_e32 v174, 0xbb800000, v203
	v_fmac_f32_e32 v172, 0xbb800000, v203
	v_fmac_f32_e32 v177, 0xbb800000, v204
	v_fmac_f32_e32 v179, 0xbb800000, v204
	v_fmac_f32_e32 v178, 0xbb800000, v204
	v_fmac_f32_e32 v176, 0xbb800000, v204
	v_fmac_f32_e32 v181, 0xbb800000, v205
	v_fmac_f32_e32 v183, 0xbb800000, v205
	v_fmac_f32_e32 v182, 0xbb800000, v205
	v_fmac_f32_e32 v180, 0xbb800000, v205
	v_fmac_f32_e32 v185, 0xbb800000, v206
	v_fmac_f32_e32 v187, 0xbb800000, v206
	v_fmac_f32_e32 v186, 0xbb800000, v206
	v_fmac_f32_e32 v184, 0xbb800000, v206
	v_fmac_f32_e32 v189, 0xbb800000, v207
	v_fmac_f32_e32 v191, 0xbb800000, v207
	v_fmac_f32_e32 v190, 0xbb800000, v207
	v_fmac_f32_e32 v188, 0xbb800000, v207
	v_mul_f32_e32 v208, v128, v128
	v_mul_f32_e32 v209, v129, v129
	v_mul_f32_e32 v210, v130, v130
	v_mul_f32_e32 v211, v131, v131
	v_add_f32_e32 v208, v209, v208
	v_add_f32_e32 v210, v210, v211
	v_add_f32_e32 v192, v208, v210
	v_mul_f32_e32 v208, v132, v132
	v_mul_f32_e32 v209, v133, v133
	v_mul_f32_e32 v210, v134, v134
	v_mul_f32_e32 v211, v135, v135
	v_add_f32_e32 v208, v209, v208
	v_add_f32_e32 v210, v210, v211
	v_add_f32_e32 v193, v208, v210
	v_mul_f32_e32 v208, v136, v136
	v_mul_f32_e32 v209, v137, v137
	v_mul_f32_e32 v210, v138, v138
	v_mul_f32_e32 v211, v139, v139
	v_add_f32_e32 v208, v209, v208
	v_add_f32_e32 v210, v210, v211
	v_add_f32_e32 v194, v208, v210
	v_mul_f32_e32 v208, v140, v140
	v_mul_f32_e32 v209, v141, v141
; __device__ __forceinline__ void sg_unit(const Params& P, int l, int chunk, char* shm, float* ssb) {
;     ...
;         v = v - mean; const f32x4 sq = v * v;
;         const float rstd = 1.f / sqrtf(wave_sum((sq[0] + sq[1]) + (sq[2] + sq[3])) * (1.f / 256.f) + LN_EPS);
	v_mul_f32_e32 v210, v142, v142
	v_mul_f32_e32 v211, v143, v143
	v_add_f32_e32 v208, v209, v208
	v_add_f32_e32 v210, v210, v211
	v_add_f32_e32 v195, v208, v210
	v_mul_f32_e32 v208, v144, v144
	v_mul_f32_e32 v209, v145, v145
	v_mul_f32_e32 v210, v146, v146
	v_mul_f32_e32 v211, v147, v147
	v_add_f32_e32 v208, v209, v208
	v_add_f32_e32 v210, v210, v211
	v_add_f32_e32 v196, v208, v210
	v_mul_f32_e32 v208, v148, v148
	v_mul_f32_e32 v209, v149, v149
	v_mul_f32_e32 v210, v150, v150
	v_mul_f32_e32 v211, v151, v151
	v_add_f32_e32 v208, v209, v208
	v_add_f32_e32 v210, v210, v211
	v_add_f32_e32 v197, v208, v210
	v_mul_f32_e32 v208, v152, v152
	v_mul_f32_e32 v209, v153, v153
	v_mul_f32_e32 v210, v154, v154
	v_mul_f32_e32 v211, v155, v155
	v_add_f32_e32 v208, v209, v208
	v_add_f32_e32 v210, v210, v211
	v_add_f32_e32 v198, v208, v210
	v_mul_f32_e32 v208, v156, v156
	v_mul_f32_e32 v209, v157, v157
	v_mul_f32_e32 v210, v158, v158
	v_mul_f32_e32 v211, v159, v159
	v_add_f32_e32 v208, v209, v208
	v_add_f32_e32 v210, v210, v211
	v_add_f32_e32 v199, v208, v210
	v_mul_f32_e32 v208, v160, v160
	v_mul_f32_e32 v209, v161, v161
	v_mul_f32_e32 v210, v162, v162
	v_mul_f32_e32 v211, v163, v163
	v_add_f32_e32 v208, v209, v208
	v_add_f32_e32 v210, v210, v211
	v_add_f32_e32 v200, v208, v210
	v_mul_f32_e32 v208, v164, v164
	v_mul_f32_e32 v209, v165, v165
	v_mul_f32_e32 v210, v166, v166
	v_mul_f32_e32 v211, v167, v167
	v_add_f32_e32 v208, v209, v208
	v_add_f32_e32 v210, v210, v211
	v_add_f32_e32 v201, v208, v210
	v_mul_f32_e32 v208, v168, v168
	v_mul_f32_e32 v209, v169, v169
	v_mul_f32_e32 v210, v170, v170
	v_mul_f32_e32 v211, v171, v171
	v_add_f32_e32 v208, v209, v208
	v_add_f32_e32 v210, v210, v211
	v_add_f32_e32 v202, v208, v210
	v_mul_f32_e32 v208, v172, v172
	v_mul_f32_e32 v209, v173, v173
	v_mul_f32_e32 v210, v174, v174
	v_mul_f32_e32 v211, v175, v175
	v_add_f32_e32 v208, v209, v208
	v_add_f32_e32 v210, v210, v211
	v_add_f32_e32 v203, v208, v210
	v_mul_f32_e32 v208, v176, v176
	v_mul_f32_e32 v209, v177, v177
	v_mul_f32_e32 v210, v178, v178
	v_mul_f32_e32 v211, v179, v179
	v_add_f32_e32 v208, v209, v208
	v_add_f32_e32 v210, v210, v211
	v_add_f32_e32 v204, v208, v210
	v_mul_f32_e32 v208, v180, v180
	v_mul_f32_e32 v209, v181, v181
	v_mul_f32_e32 v210, v182, v182
	v_mul_f32_e32 v211, v183, v183
	v_add_f32_e32 v208, v209, v208
	v_add_f32_e32 v210, v210, v211
	v_add_f32_e32 v205, v208, v210
	v_mul_f32_e32 v208, v184, v184
	v_mul_f32_e32 v209, v185, v185
	v_mul_f32_e32 v210, v186, v186
	v_mul_f32_e32 v211, v187, v187
	v_add_f32_e32 v208, v209, v208
	v_add_f32_e32 v210, v210, v211
	v_add_f32_e32 v206, v208, v210
	v_mul_f32_e32 v208, v188, v188
	v_mul_f32_e32 v209, v189, v189
	v_mul_f32_e32 v210, v190, v190
	v_mul_f32_e32 v211, v191, v191
	v_add_f32_e32 v208, v209, v208
	v_add_f32_e32 v210, v210, v211
	v_add_f32_e32 v207, v208, v210
	ds_bpermute_b32 v96, v17, v192
	ds_bpermute_b32 v97, v17, v193
	ds_bpermute_b32 v98, v17, v194
	ds_bpermute_b32 v99, v17, v195
	ds_bpermute_b32 v100, v17, v196
	ds_bpermute_b32 v101, v17, v197
	ds_bpermute_b32 v102, v17, v198
	ds_bpermute_b32 v103, v17, v199
	ds_bpermute_b32 v104, v17, v200
	ds_bpermute_b32 v105, v17, v201
	ds_bpermute_b32 v106, v17, v202
	ds_bpermute_b32 v107, v17, v203
	ds_bpermute_b32 v108, v17, v204
	ds_bpermute_b32 v109, v17, v205
	ds_bpermute_b32 v110, v17, v206
	ds_bpermute_b32 v111, v17, v207
	s_waitcnt lgkmcnt(8)
	v_add_f32_e32 v192, v192, v96
	v_add_f32_e32 v193, v193, v97
	v_add_f32_e32 v194, v194, v98
	v_add_f32_e32 v195, v195, v99
	v_add_f32_e32 v196, v196, v100
	v_add_f32_e32 v197, v197, v101
	v_add_f32_e32 v198, v198, v102
	v_add_f32_e32 v199, v199, v103
	s_waitcnt lgkmcnt(0)
	v_add_f32_e32 v200, v200, v104
	v_add_f32_e32 v201, v201, v105
	v_add_f32_e32 v202, v202, v106
	v_add_f32_e32 v203, v203, v107
	v_add_f32_e32 v204, v204, v108
	v_add_f32_e32 v205, v205, v109
	v_add_f32_e32 v206, v206, v110
	v_add_f32_e32 v207, v207, v111
	ds_bpermute_b32 v96, v83, v192
	ds_bpermute_b32 v97, v83, v193
	ds_bpermute_b32 v98, v83, v194
	ds_bpermute_b32 v99, v83, v195
	ds_bpermute_b32 v100, v83, v196
	ds_bpermute_b32 v101, v83, v197
	ds_bpermute_b32 v102, v83, v198
	ds_bpermute_b32 v103, v83, v199
	ds_bpermute_b32 v104, v83, v200
	ds_bpermute_b32 v105, v83, v201
	ds_bpermute_b32 v106, v83, v202
	ds_bpermute_b32 v107, v83, v203
	ds_bpermute_b32 v108, v83, v204
	ds_bpermute_b32 v109, v83, v205
	ds_bpermute_b32 v110, v83, v206
	ds_bpermute_b32 v111, v83, v207
	s_waitcnt lgkmcnt(8)
	v_add_f32_e32 v192, v192, v96
	v_add_f32_e32 v193, v193, v97
	v_add_f32_e32 v194, v194, v98
	v_add_f32_e32 v195, v195, v99
	v_add_f32_e32 v196, v196, v100
	v_add_f32_e32 v197, v197, v101
	v_add_f32_e32 v198, v198, v102
	v_add_f32_e32 v199, v199, v103
	s_waitcnt lgkmcnt(0)
	v_add_f32_e32 v200, v200, v104
	v_add_f32_e32 v201, v201, v105
	v_add_f32_e32 v202, v202, v106
	v_add_f32_e32 v203, v203, v107
	v_add_f32_e32 v204, v204, v108
	v_add_f32_e32 v205, v205, v109
	v_add_f32_e32 v206, v206, v110
	v_add_f32_e32 v207, v207, v111
	ds_bpermute_b32 v96, v82, v192
	ds_bpermute_b32 v97, v82, v193
	ds_bpermute_b32 v98, v82, v194
	ds_bpermute_b32 v99, v82, v195
	ds_bpermute_b32 v100, v82, v196
	ds_bpermute_b32 v101, v82, v197
	ds_bpermute_b32 v102, v82, v198
	ds_bpermute_b32 v103, v82, v199
	ds_bpermute_b32 v104, v82, v200
	ds_bpermute_b32 v105, v82, v201
	ds_bpermute_b32 v106, v82, v202
	ds_bpermute_b32 v107, v82, v203
	ds_bpermute_b32 v108, v82, v204
	ds_bpermute_b32 v109, v82, v205
	ds_bpermute_b32 v110, v82, v206
	ds_bpermute_b32 v111, v82, v207
	s_waitcnt lgkmcnt(8)
; __device__ __forceinline__ unsigned cvtpk_s(float lo, float hi) { typedef __bf16 bf16x2_t __attribute__((ext_vector_type(2))); f32x2 v = {lo, hi}; bf16x2_t b = __builtin_convertvector(v, bf16x2_t); return __builtin_bit_cast(unsigned, b); }
; __device__ __forceinline__ void sg_unit(const Params& P, int l, int chunk, char* shm, float* ssb) {
;     ...
;         const float mean = wave_sum((v[0] + v[1]) + (v[2] + v[3])) * (1.f / 256.f);
;         v = v - mean; const f32x4 sq = v * v;
;         const float rstd = 1.f / sqrtf(wave_sum((sq[0] + sq[1]) + (sq[2] + sq[3])) * (1.f / 256.f) + LN_EPS);
;         v = v * rstd * g4;
; #pragma unroll
;         for (int j = 0; j < 4; ++j) vt[(4 * lane + j) * SG_VT_PITCH + q] = (bf16_t)(at::cvtpk_s(v[j], 0.f) & 0xffffu);
	v_add_f32_e32 v192, v192, v96
	v_add_f32_e32 v193, v193, v97
	v_add_f32_e32 v194, v194, v98
	v_add_f32_e32 v195, v195, v99
	v_add_f32_e32 v196, v196, v100
	v_add_f32_e32 v197, v197, v101
	v_add_f32_e32 v198, v198, v102
	v_add_f32_e32 v199, v199, v103
	s_waitcnt lgkmcnt(0)
	v_add_f32_e32 v200, v200, v104
	v_add_f32_e32 v201, v201, v105
	v_add_f32_e32 v202, v202, v106
	v_add_f32_e32 v203, v203, v107
	v_add_f32_e32 v204, v204, v108
	v_add_f32_e32 v205, v205, v109
	v_add_f32_e32 v206, v206, v110
	v_add_f32_e32 v207, v207, v111
	ds_bpermute_b32 v96, v14, v192
	ds_bpermute_b32 v97, v14, v193
	ds_bpermute_b32 v98, v14, v194
	ds_bpermute_b32 v99, v14, v195
	ds_bpermute_b32 v100, v14, v196
	ds_bpermute_b32 v101, v14, v197
	ds_bpermute_b32 v102, v14, v198
	ds_bpermute_b32 v103, v14, v199
	ds_bpermute_b32 v104, v14, v200
	ds_bpermute_b32 v105, v14, v201
	ds_bpermute_b32 v106, v14, v202
	ds_bpermute_b32 v107, v14, v203
	ds_bpermute_b32 v108, v14, v204
	ds_bpermute_b32 v109, v14, v205
	ds_bpermute_b32 v110, v14, v206
	ds_bpermute_b32 v111, v14, v207
	s_waitcnt lgkmcnt(8)
	v_add_f32_e32 v192, v192, v96
	v_add_f32_e32 v193, v193, v97
	v_add_f32_e32 v194, v194, v98
	v_add_f32_e32 v195, v195, v99
	v_add_f32_e32 v196, v196, v100
	v_add_f32_e32 v197, v197, v101
	v_add_f32_e32 v198, v198, v102
	v_add_f32_e32 v199, v199, v103
	s_waitcnt lgkmcnt(0)
	v_add_f32_e32 v200, v200, v104
	v_add_f32_e32 v201, v201, v105
	v_add_f32_e32 v202, v202, v106
	v_add_f32_e32 v203, v203, v107
	v_add_f32_e32 v204, v204, v108
	v_add_f32_e32 v205, v205, v109
	v_add_f32_e32 v206, v206, v110
	v_add_f32_e32 v207, v207, v111
	ds_bpermute_b32 v96, v15, v192
	ds_bpermute_b32 v97, v15, v193
	ds_bpermute_b32 v98, v15, v194
	ds_bpermute_b32 v99, v15, v195
	ds_bpermute_b32 v100, v15, v196
	ds_bpermute_b32 v101, v15, v197
	ds_bpermute_b32 v102, v15, v198
	ds_bpermute_b32 v103, v15, v199
	ds_bpermute_b32 v104, v15, v200
	ds_bpermute_b32 v105, v15, v201
	ds_bpermute_b32 v106, v15, v202
	ds_bpermute_b32 v107, v15, v203
	ds_bpermute_b32 v108, v15, v204
	ds_bpermute_b32 v109, v15, v205
	ds_bpermute_b32 v110, v15, v206
	ds_bpermute_b32 v111, v15, v207
	s_waitcnt lgkmcnt(8)
	v_add_f32_e32 v192, v192, v96
	v_add_f32_e32 v193, v193, v97
	v_add_f32_e32 v194, v194, v98
	v_add_f32_e32 v195, v195, v99
	v_add_f32_e32 v196, v196, v100
	v_add_f32_e32 v197, v197, v101
	v_add_f32_e32 v198, v198, v102
	v_add_f32_e32 v199, v199, v103
	s_waitcnt lgkmcnt(0)
	v_add_f32_e32 v200, v200, v104
	v_add_f32_e32 v201, v201, v105
	v_add_f32_e32 v202, v202, v106
	v_add_f32_e32 v203, v203, v107
	v_add_f32_e32 v204, v204, v108
	v_add_f32_e32 v205, v205, v109
	v_add_f32_e32 v206, v206, v110
	v_add_f32_e32 v207, v207, v111
	ds_bpermute_b32 v96, v18, v192
	ds_bpermute_b32 v97, v18, v193
	ds_bpermute_b32 v98, v18, v194
	ds_bpermute_b32 v99, v18, v195
	ds_bpermute_b32 v100, v18, v196
	ds_bpermute_b32 v101, v18, v197
	ds_bpermute_b32 v102, v18, v198
	ds_bpermute_b32 v103, v18, v199
	ds_bpermute_b32 v104, v18, v200
	ds_bpermute_b32 v105, v18, v201
	ds_bpermute_b32 v106, v18, v202
	ds_bpermute_b32 v107, v18, v203
	ds_bpermute_b32 v108, v18, v204
	ds_bpermute_b32 v109, v18, v205
	ds_bpermute_b32 v110, v18, v206
	ds_bpermute_b32 v111, v18, v207
	s_waitcnt lgkmcnt(8)
	v_add_f32_e32 v192, v192, v96
	v_add_f32_e32 v193, v193, v97
	v_add_f32_e32 v194, v194, v98
	v_add_f32_e32 v195, v195, v99
	v_add_f32_e32 v196, v196, v100
	v_add_f32_e32 v197, v197, v101
	v_add_f32_e32 v198, v198, v102
	v_add_f32_e32 v199, v199, v103
	s_waitcnt lgkmcnt(0)
	v_add_f32_e32 v200, v200, v104
	v_add_f32_e32 v201, v201, v105
	v_add_f32_e32 v202, v202, v106
	v_add_f32_e32 v203, v203, v107
	v_add_f32_e32 v204, v204, v108
	v_add_f32_e32 v205, v205, v109
	v_add_f32_e32 v206, v206, v110
	v_add_f32_e32 v207, v207, v111
	v_fmamk_f32 v192, v192, 0x3b800000, v216
	v_cmp_gt_f32_e32 vcc, s69, v192
	v_mul_f32_e32 v96, 0x4f800000, v192
	s_nop 0
	v_cndmask_b32_e32 v192, v192, v96, vcc
	v_sqrt_f32_e32 v96, v192
	s_nop 0
	v_add_u32_e32 v97, -1, v96
	v_fma_f32 v98, -v97, v96, v192
	v_cmp_ge_f32_e64 s[0:1], 0, v98
	v_add_u32_e32 v98, 1, v96
	s_nop 0
	v_cndmask_b32_e64 v97, v96, v97, s[0:1]
	v_fma_f32 v96, -v98, v96, v192
	v_cmp_lt_f32_e64 s[0:1], 0, v96
	s_nop 1
	v_cndmask_b32_e64 v96, v97, v98, s[0:1]
	v_mul_f32_e32 v97, 0x37800000, v96
	v_cndmask_b32_e32 v96, v96, v97, vcc
	v_cmp_class_f32_e32 vcc, v192, v217
	s_nop 1
	v_cndmask_b32_e32 v192, v96, v192, vcc
	v_div_scale_f32 v96, s[0:1], v192, v192, 1.0
	v_rcp_f32_e32 v97, v96
	s_nop 0
	v_fma_f32 v98, -v96, v97, 1.0
	v_fmac_f32_e32 v97, v98, v97
	v_div_scale_f32 v98, vcc, 1.0, v192, 1.0
	v_mul_f32_e32 v99, v98, v97
	v_fma_f32 v100, -v96, v99, v98
	v_fmac_f32_e32 v99, v100, v97
	v_fma_f32 v96, -v96, v99, v98
	v_div_fmas_f32 v96, v96, v97, v99
	v_div_fixup_f32 v192, v96, v192, 1.0
	v_mul_f32_e32 v128, v128, v192
	v_mul_f32_e32 v129, v129, v192
	v_mul_f32_e32 v130, v130, v192
	v_mul_f32_e32 v131, v131, v192
	v_mul_f32_e32 v96, v2, v128
	v_cvt_pk_bf16_f32 v96, v96, s0
	v_mul_f32_e32 v97, v3, v129
	v_cvt_pk_bf16_f32 v97, v97, s0
	v_mul_f32_e32 v98, v4, v130
	v_cvt_pk_bf16_f32 v98, v98, s0
	v_mul_f32_e32 v99, v5, v131
	v_cvt_pk_bf16_f32 v99, v99, s0
	ds_write_b16 v19, v96 offset:0
	ds_write_b16 v19, v97 offset:272
	ds_write_b16 v19, v98 offset:544
	ds_write_b16 v19, v99 offset:816
	v_fmamk_f32 v193, v193, 0x3b800000, v216
	v_cmp_gt_f32_e32 vcc, s69, v193
	v_mul_f32_e32 v96, 0x4f800000, v193
	s_nop 0
	v_cndmask_b32_e32 v193, v193, v96, vcc
	v_sqrt_f32_e32 v96, v193
	s_nop 0
	v_add_u32_e32 v97, -1, v96
	v_fma_f32 v98, -v97, v96, v193
	v_cmp_ge_f32_e64 s[0:1], 0, v98
	v_add_u32_e32 v98, 1, v96
	s_nop 0
	v_cndmask_b32_e64 v97, v96, v97, s[0:1]
; __device__ __forceinline__ unsigned cvtpk_s(float lo, float hi) { typedef __bf16 bf16x2_t __attribute__((ext_vector_type(2))); f32x2 v = {lo, hi}; bf16x2_t b = __builtin_convertvector(v, bf16x2_t); return __builtin_bit_cast(unsigned, b); }
; __device__ __forceinline__ void sg_unit(const Params& P, int l, int chunk, char* shm, float* ssb) {
;     ...
;         const float rstd = 1.f / sqrtf(wave_sum((sq[0] + sq[1]) + (sq[2] + sq[3])) * (1.f / 256.f) + LN_EPS);
;         v = v * rstd * g4;
; #pragma unroll
;         for (int j = 0; j < 4; ++j) vt[(4 * lane + j) * SG_VT_PITCH + q] = (bf16_t)(at::cvtpk_s(v[j], 0.f) & 0xffffu);
	v_fma_f32 v96, -v98, v96, v193
	v_cmp_lt_f32_e64 s[0:1], 0, v96
	s_nop 1
	v_cndmask_b32_e64 v96, v97, v98, s[0:1]
	v_mul_f32_e32 v97, 0x37800000, v96
	v_cndmask_b32_e32 v96, v96, v97, vcc
	v_cmp_class_f32_e32 vcc, v193, v217
	s_nop 1
	v_cndmask_b32_e32 v193, v96, v193, vcc
	v_div_scale_f32 v96, s[0:1], v193, v193, 1.0
	v_rcp_f32_e32 v97, v96
	s_nop 0
	v_fma_f32 v98, -v96, v97, 1.0
	v_fmac_f32_e32 v97, v98, v97
	v_div_scale_f32 v98, vcc, 1.0, v193, 1.0
	v_mul_f32_e32 v99, v98, v97
	v_fma_f32 v100, -v96, v99, v98
	v_fmac_f32_e32 v99, v100, v97
	v_fma_f32 v96, -v96, v99, v98
	v_div_fmas_f32 v96, v96, v97, v99
	v_div_fixup_f32 v193, v96, v193, 1.0
	v_mul_f32_e32 v132, v132, v193
	v_mul_f32_e32 v133, v133, v193
	v_mul_f32_e32 v134, v134, v193
	v_mul_f32_e32 v135, v135, v193
	v_mul_f32_e32 v96, v2, v132
	v_cvt_pk_bf16_f32 v96, v96, s0
	v_mul_f32_e32 v97, v3, v133
	v_cvt_pk_bf16_f32 v97, v97, s0
	v_mul_f32_e32 v98, v4, v134
	v_cvt_pk_bf16_f32 v98, v98, s0
	v_mul_f32_e32 v99, v5, v135
	v_cvt_pk_bf16_f32 v99, v99, s0
	ds_write_b16 v19, v96 offset:2
	ds_write_b16 v19, v97 offset:274
	ds_write_b16 v19, v98 offset:546
	ds_write_b16 v19, v99 offset:818
	v_fmamk_f32 v194, v194, 0x3b800000, v216
	v_cmp_gt_f32_e32 vcc, s69, v194
	v_mul_f32_e32 v96, 0x4f800000, v194
	s_nop 0
	v_cndmask_b32_e32 v194, v194, v96, vcc
	v_sqrt_f32_e32 v96, v194
	s_nop 0
	v_add_u32_e32 v97, -1, v96
	v_fma_f32 v98, -v97, v96, v194
	v_cmp_ge_f32_e64 s[0:1], 0, v98
	v_add_u32_e32 v98, 1, v96
	s_nop 0
	v_cndmask_b32_e64 v97, v96, v97, s[0:1]
	v_fma_f32 v96, -v98, v96, v194
	v_cmp_lt_f32_e64 s[0:1], 0, v96
	s_nop 1
	v_cndmask_b32_e64 v96, v97, v98, s[0:1]
	v_mul_f32_e32 v97, 0x37800000, v96
	v_cndmask_b32_e32 v96, v96, v97, vcc
	v_cmp_class_f32_e32 vcc, v194, v217
	s_nop 1
	v_cndmask_b32_e32 v194, v96, v194, vcc
	v_div_scale_f32 v96, s[0:1], v194, v194, 1.0
	v_rcp_f32_e32 v97, v96
	s_nop 0
	v_fma_f32 v98, -v96, v97, 1.0
	v_fmac_f32_e32 v97, v98, v97
	v_div_scale_f32 v98, vcc, 1.0, v194, 1.0
	v_mul_f32_e32 v99, v98, v97
	v_fma_f32 v100, -v96, v99, v98
	v_fmac_f32_e32 v99, v100, v97
	v_fma_f32 v96, -v96, v99, v98
	v_div_fmas_f32 v96, v96, v97, v99
	v_div_fixup_f32 v194, v96, v194, 1.0
	v_mul_f32_e32 v136, v136, v194
	v_mul_f32_e32 v137, v137, v194
	v_mul_f32_e32 v138, v138, v194
	v_mul_f32_e32 v139, v139, v194
	v_mul_f32_e32 v96, v2, v136
	v_cvt_pk_bf16_f32 v96, v96, s0
	v_mul_f32_e32 v97, v3, v137
	v_cvt_pk_bf16_f32 v97, v97, s0
	v_mul_f32_e32 v98, v4, v138
	v_cvt_pk_bf16_f32 v98, v98, s0
	v_mul_f32_e32 v99, v5, v139
	v_cvt_pk_bf16_f32 v99, v99, s0
	ds_write_b16 v19, v96 offset:4
	ds_write_b16 v19, v97 offset:276
	ds_write_b16 v19, v98 offset:548
	ds_write_b16 v19, v99 offset:820
	v_fmamk_f32 v195, v195, 0x3b800000, v216
	v_cmp_gt_f32_e32 vcc, s69, v195
	v_mul_f32_e32 v96, 0x4f800000, v195
	s_nop 0
	v_cndmask_b32_e32 v195, v195, v96, vcc
	v_sqrt_f32_e32 v96, v195
	s_nop 0
	v_add_u32_e32 v97, -1, v96
	v_fma_f32 v98, -v97, v96, v195
	v_cmp_ge_f32_e64 s[0:1], 0, v98
	v_add_u32_e32 v98, 1, v96
	s_nop 0
	v_cndmask_b32_e64 v97, v96, v97, s[0:1]
	v_fma_f32 v96, -v98, v96, v195
	v_cmp_lt_f32_e64 s[0:1], 0, v96
	s_nop 1
	v_cndmask_b32_e64 v96, v97, v98, s[0:1]
	v_mul_f32_e32 v97, 0x37800000, v96
	v_cndmask_b32_e32 v96, v96, v97, vcc
	v_cmp_class_f32_e32 vcc, v195, v217
	s_nop 1
	v_cndmask_b32_e32 v195, v96, v195, vcc
	v_div_scale_f32 v96, s[0:1], v195, v195, 1.0
	v_rcp_f32_e32 v97, v96
	s_nop 0
	v_fma_f32 v98, -v96, v97, 1.0
	v_fmac_f32_e32 v97, v98, v97
	v_div_scale_f32 v98, vcc, 1.0, v195, 1.0
	v_mul_f32_e32 v99, v98, v97
	v_fma_f32 v100, -v96, v99, v98
	v_fmac_f32_e32 v99, v100, v97
	v_fma_f32 v96, -v96, v99, v98
	v_div_fmas_f32 v96, v96, v97, v99
	v_div_fixup_f32 v195, v96, v195, 1.0
	v_mul_f32_e32 v140, v140, v195
	v_mul_f32_e32 v141, v141, v195
	v_mul_f32_e32 v142, v142, v195
	v_mul_f32_e32 v143, v143, v195
	v_mul_f32_e32 v96, v2, v140
	v_cvt_pk_bf16_f32 v96, v96, s0
	v_mul_f32_e32 v97, v3, v141
	v_cvt_pk_bf16_f32 v97, v97, s0
	v_mul_f32_e32 v98, v4, v142
	v_cvt_pk_bf16_f32 v98, v98, s0
	v_mul_f32_e32 v99, v5, v143
	v_cvt_pk_bf16_f32 v99, v99, s0
	ds_write_b16 v19, v96 offset:6
	ds_write_b16 v19, v97 offset:278
	ds_write_b16 v19, v98 offset:550
	ds_write_b16 v19, v99 offset:822
	v_fmamk_f32 v196, v196, 0x3b800000, v216
	v_cmp_gt_f32_e32 vcc, s69, v196
	v_mul_f32_e32 v96, 0x4f800000, v196
	s_nop 0
	v_cndmask_b32_e32 v196, v196, v96, vcc
	v_sqrt_f32_e32 v96, v196
	s_nop 0
	v_add_u32_e32 v97, -1, v96
	v_fma_f32 v98, -v97, v96, v196
	v_cmp_ge_f32_e64 s[0:1], 0, v98
	v_add_u32_e32 v98, 1, v96
	s_nop 0
	v_cndmask_b32_e64 v97, v96, v97, s[0:1]
	v_fma_f32 v96, -v98, v96, v196
	v_cmp_lt_f32_e64 s[0:1], 0, v96
	s_nop 1
	v_cndmask_b32_e64 v96, v97, v98, s[0:1]
	v_mul_f32_e32 v97, 0x37800000, v96
	v_cndmask_b32_e32 v96, v96, v97, vcc
	v_cmp_class_f32_e32 vcc, v196, v217
	s_nop 1
	v_cndmask_b32_e32 v196, v96, v196, vcc
	v_div_scale_f32 v96, s[0:1], v196, v196, 1.0
	v_rcp_f32_e32 v97, v96
	s_nop 0
	v_fma_f32 v98, -v96, v97, 1.0
	v_fmac_f32_e32 v97, v98, v97
	v_div_scale_f32 v98, vcc, 1.0, v196, 1.0
	v_mul_f32_e32 v99, v98, v97
	v_fma_f32 v100, -v96, v99, v98
	v_fmac_f32_e32 v99, v100, v97
	v_fma_f32 v96, -v96, v99, v98
	v_div_fmas_f32 v96, v96, v97, v99
	v_div_fixup_f32 v196, v96, v196, 1.0
	v_mul_f32_e32 v144, v144, v196
	v_mul_f32_e32 v145, v145, v196
	v_mul_f32_e32 v146, v146, v196
	v_mul_f32_e32 v147, v147, v196
	v_mul_f32_e32 v96, v2, v144
	v_cvt_pk_bf16_f32 v96, v96, s0
	v_mul_f32_e32 v97, v3, v145
	v_cvt_pk_bf16_f32 v97, v97, s0
	v_mul_f32_e32 v98, v4, v146
	v_cvt_pk_bf16_f32 v98, v98, s0
	v_mul_f32_e32 v99, v5, v147
	v_cvt_pk_bf16_f32 v99, v99, s0
	ds_write_b16 v19, v96 offset:8
; __device__ __forceinline__ unsigned cvtpk_s(float lo, float hi) { typedef __bf16 bf16x2_t __attribute__((ext_vector_type(2))); f32x2 v = {lo, hi}; bf16x2_t b = __builtin_convertvector(v, bf16x2_t); return __builtin_bit_cast(unsigned, b); }
; __device__ __forceinline__ void sg_unit(const Params& P, int l, int chunk, char* shm, float* ssb) {
;     ...
;         const float rstd = 1.f / sqrtf(wave_sum((sq[0] + sq[1]) + (sq[2] + sq[3])) * (1.f / 256.f) + LN_EPS);
;         v = v * rstd * g4;
; #pragma unroll
;         for (int j = 0; j < 4; ++j) vt[(4 * lane + j) * SG_VT_PITCH + q] = (bf16_t)(at::cvtpk_s(v[j], 0.f) & 0xffffu);
	ds_write_b16 v19, v97 offset:280
	ds_write_b16 v19, v98 offset:552
	ds_write_b16 v19, v99 offset:824
	v_fmamk_f32 v197, v197, 0x3b800000, v216
	v_cmp_gt_f32_e32 vcc, s69, v197
	v_mul_f32_e32 v96, 0x4f800000, v197
	s_nop 0
	v_cndmask_b32_e32 v197, v197, v96, vcc
	v_sqrt_f32_e32 v96, v197
	s_nop 0
	v_add_u32_e32 v97, -1, v96
	v_fma_f32 v98, -v97, v96, v197
	v_cmp_ge_f32_e64 s[0:1], 0, v98
	v_add_u32_e32 v98, 1, v96
	s_nop 0
	v_cndmask_b32_e64 v97, v96, v97, s[0:1]
	v_fma_f32 v96, -v98, v96, v197
	v_cmp_lt_f32_e64 s[0:1], 0, v96
	s_nop 1
	v_cndmask_b32_e64 v96, v97, v98, s[0:1]
	v_mul_f32_e32 v97, 0x37800000, v96
	v_cndmask_b32_e32 v96, v96, v97, vcc
	v_cmp_class_f32_e32 vcc, v197, v217
	s_nop 1
	v_cndmask_b32_e32 v197, v96, v197, vcc
	v_div_scale_f32 v96, s[0:1], v197, v197, 1.0
	v_rcp_f32_e32 v97, v96
	s_nop 0
	v_fma_f32 v98, -v96, v97, 1.0
	v_fmac_f32_e32 v97, v98, v97
	v_div_scale_f32 v98, vcc, 1.0, v197, 1.0
	v_mul_f32_e32 v99, v98, v97
	v_fma_f32 v100, -v96, v99, v98
	v_fmac_f32_e32 v99, v100, v97
	v_fma_f32 v96, -v96, v99, v98
	v_div_fmas_f32 v96, v96, v97, v99
	v_div_fixup_f32 v197, v96, v197, 1.0
	v_mul_f32_e32 v148, v148, v197
	v_mul_f32_e32 v149, v149, v197
	v_mul_f32_e32 v150, v150, v197
	v_mul_f32_e32 v151, v151, v197
	v_mul_f32_e32 v96, v2, v148
	v_cvt_pk_bf16_f32 v96, v96, s0
	v_mul_f32_e32 v97, v3, v149
	v_cvt_pk_bf16_f32 v97, v97, s0
	v_mul_f32_e32 v98, v4, v150
	v_cvt_pk_bf16_f32 v98, v98, s0
	v_mul_f32_e32 v99, v5, v151
	v_cvt_pk_bf16_f32 v99, v99, s0
	ds_write_b16 v19, v96 offset:10
	ds_write_b16 v19, v97 offset:282
	ds_write_b16 v19, v98 offset:554
	ds_write_b16 v19, v99 offset:826
	v_fmamk_f32 v198, v198, 0x3b800000, v216
	v_cmp_gt_f32_e32 vcc, s69, v198
	v_mul_f32_e32 v96, 0x4f800000, v198
	s_nop 0
	v_cndmask_b32_e32 v198, v198, v96, vcc
	v_sqrt_f32_e32 v96, v198
	s_nop 0
	v_add_u32_e32 v97, -1, v96
	v_fma_f32 v98, -v97, v96, v198
	v_cmp_ge_f32_e64 s[0:1], 0, v98
	v_add_u32_e32 v98, 1, v96
	s_nop 0
	v_cndmask_b32_e64 v97, v96, v97, s[0:1]
	v_fma_f32 v96, -v98, v96, v198
	v_cmp_lt_f32_e64 s[0:1], 0, v96
	s_nop 1
	v_cndmask_b32_e64 v96, v97, v98, s[0:1]
	v_mul_f32_e32 v97, 0x37800000, v96
	v_cndmask_b32_e32 v96, v96, v97, vcc
	v_cmp_class_f32_e32 vcc, v198, v217
	s_nop 1
	v_cndmask_b32_e32 v198, v96, v198, vcc
	v_div_scale_f32 v96, s[0:1], v198, v198, 1.0
	v_rcp_f32_e32 v97, v96
	s_nop 0
	v_fma_f32 v98, -v96, v97, 1.0
	v_fmac_f32_e32 v97, v98, v97
	v_div_scale_f32 v98, vcc, 1.0, v198, 1.0
	v_mul_f32_e32 v99, v98, v97
	v_fma_f32 v100, -v96, v99, v98
	v_fmac_f32_e32 v99, v100, v97
	v_fma_f32 v96, -v96, v99, v98
	v_div_fmas_f32 v96, v96, v97, v99
	v_div_fixup_f32 v198, v96, v198, 1.0
	v_mul_f32_e32 v152, v152, v198
	v_mul_f32_e32 v153, v153, v198
	v_mul_f32_e32 v154, v154, v198
	v_mul_f32_e32 v155, v155, v198
	v_mul_f32_e32 v96, v2, v152
	v_cvt_pk_bf16_f32 v96, v96, s0
	v_mul_f32_e32 v97, v3, v153
	v_cvt_pk_bf16_f32 v97, v97, s0
	v_mul_f32_e32 v98, v4, v154
	v_cvt_pk_bf16_f32 v98, v98, s0
	v_mul_f32_e32 v99, v5, v155
	v_cvt_pk_bf16_f32 v99, v99, s0
	ds_write_b16 v19, v96 offset:12
	ds_write_b16 v19, v97 offset:284
	ds_write_b16 v19, v98 offset:556
	ds_write_b16 v19, v99 offset:828
	v_fmamk_f32 v199, v199, 0x3b800000, v216
	v_cmp_gt_f32_e32 vcc, s69, v199
	v_mul_f32_e32 v96, 0x4f800000, v199
	s_nop 0
	v_cndmask_b32_e32 v199, v199, v96, vcc
	v_sqrt_f32_e32 v96, v199
	s_nop 0
	v_add_u32_e32 v97, -1, v96
	v_fma_f32 v98, -v97, v96, v199
	v_cmp_ge_f32_e64 s[0:1], 0, v98
	v_add_u32_e32 v98, 1, v96
	s_nop 0
	v_cndmask_b32_e64 v97, v96, v97, s[0:1]
	v_fma_f32 v96, -v98, v96, v199
	v_cmp_lt_f32_e64 s[0:1], 0, v96
	s_nop 1
	v_cndmask_b32_e64 v96, v97, v98, s[0:1]
	v_mul_f32_e32 v97, 0x37800000, v96
	v_cndmask_b32_e32 v96, v96, v97, vcc
	v_cmp_class_f32_e32 vcc, v199, v217
	s_nop 1
	v_cndmask_b32_e32 v199, v96, v199, vcc
	v_div_scale_f32 v96, s[0:1], v199, v199, 1.0
	v_rcp_f32_e32 v97, v96
	s_nop 0
	v_fma_f32 v98, -v96, v97, 1.0
	v_fmac_f32_e32 v97, v98, v97
	v_div_scale_f32 v98, vcc, 1.0, v199, 1.0
	v_mul_f32_e32 v99, v98, v97
	v_fma_f32 v100, -v96, v99, v98
	v_fmac_f32_e32 v99, v100, v97
	v_fma_f32 v96, -v96, v99, v98
	v_div_fmas_f32 v96, v96, v97, v99
	v_div_fixup_f32 v199, v96, v199, 1.0
	v_mul_f32_e32 v156, v156, v199
	v_mul_f32_e32 v157, v157, v199
	v_mul_f32_e32 v158, v158, v199
	v_mul_f32_e32 v159, v159, v199
	v_mul_f32_e32 v96, v2, v156
	v_cvt_pk_bf16_f32 v96, v96, s0
	v_mul_f32_e32 v97, v3, v157
	v_cvt_pk_bf16_f32 v97, v97, s0
	v_mul_f32_e32 v98, v4, v158
	v_cvt_pk_bf16_f32 v98, v98, s0
	v_mul_f32_e32 v99, v5, v159
	v_cvt_pk_bf16_f32 v99, v99, s0
	ds_write_b16 v19, v96 offset:14
	ds_write_b16 v19, v97 offset:286
	ds_write_b16 v19, v98 offset:558
	ds_write_b16 v19, v99 offset:830
	v_fmamk_f32 v200, v200, 0x3b800000, v216
	v_cmp_gt_f32_e32 vcc, s69, v200
	v_mul_f32_e32 v96, 0x4f800000, v200
	s_nop 0
	v_cndmask_b32_e32 v200, v200, v96, vcc
	v_sqrt_f32_e32 v96, v200
	s_nop 0
	v_add_u32_e32 v97, -1, v96
	v_fma_f32 v98, -v97, v96, v200
	v_cmp_ge_f32_e64 s[0:1], 0, v98
	v_add_u32_e32 v98, 1, v96
	s_nop 0
	v_cndmask_b32_e64 v97, v96, v97, s[0:1]
	v_fma_f32 v96, -v98, v96, v200
	v_cmp_lt_f32_e64 s[0:1], 0, v96
	s_nop 1
	v_cndmask_b32_e64 v96, v97, v98, s[0:1]
	v_mul_f32_e32 v97, 0x37800000, v96
	v_cndmask_b32_e32 v96, v96, v97, vcc
	v_cmp_class_f32_e32 vcc, v200, v217
	s_nop 1
	v_cndmask_b32_e32 v200, v96, v200, vcc
	v_div_scale_f32 v96, s[0:1], v200, v200, 1.0
	v_rcp_f32_e32 v97, v96
	s_nop 0
	v_fma_f32 v98, -v96, v97, 1.0
	v_fmac_f32_e32 v97, v98, v97
	v_div_scale_f32 v98, vcc, 1.0, v200, 1.0
	v_mul_f32_e32 v99, v98, v97
	v_fma_f32 v100, -v96, v99, v98
	v_fmac_f32_e32 v99, v100, v97
	v_fma_f32 v96, -v96, v99, v98
; __device__ __forceinline__ unsigned cvtpk_s(float lo, float hi) { typedef __bf16 bf16x2_t __attribute__((ext_vector_type(2))); f32x2 v = {lo, hi}; bf16x2_t b = __builtin_convertvector(v, bf16x2_t); return __builtin_bit_cast(unsigned, b); }
; __device__ __forceinline__ void sg_unit(const Params& P, int l, int chunk, char* shm, float* ssb) {
;     ...
;         const float rstd = 1.f / sqrtf(wave_sum((sq[0] + sq[1]) + (sq[2] + sq[3])) * (1.f / 256.f) + LN_EPS);
;         v = v * rstd * g4;
; #pragma unroll
;         for (int j = 0; j < 4; ++j) vt[(4 * lane + j) * SG_VT_PITCH + q] = (bf16_t)(at::cvtpk_s(v[j], 0.f) & 0xffffu);
	v_div_fmas_f32 v96, v96, v97, v99
	v_div_fixup_f32 v200, v96, v200, 1.0
	v_mul_f32_e32 v160, v160, v200
	v_mul_f32_e32 v161, v161, v200
	v_mul_f32_e32 v162, v162, v200
	v_mul_f32_e32 v163, v163, v200
	v_mul_f32_e32 v96, v2, v160
	v_cvt_pk_bf16_f32 v96, v96, s0
	v_mul_f32_e32 v97, v3, v161
	v_cvt_pk_bf16_f32 v97, v97, s0
	v_mul_f32_e32 v98, v4, v162
	v_cvt_pk_bf16_f32 v98, v98, s0
	v_mul_f32_e32 v99, v5, v163
	v_cvt_pk_bf16_f32 v99, v99, s0
	ds_write_b16 v19, v96 offset:16
	ds_write_b16 v19, v97 offset:288
	ds_write_b16 v19, v98 offset:560
	ds_write_b16 v19, v99 offset:832
	v_fmamk_f32 v201, v201, 0x3b800000, v216
	v_cmp_gt_f32_e32 vcc, s69, v201
	v_mul_f32_e32 v96, 0x4f800000, v201
	s_nop 0
	v_cndmask_b32_e32 v201, v201, v96, vcc
	v_sqrt_f32_e32 v96, v201
	s_nop 0
	v_add_u32_e32 v97, -1, v96
	v_fma_f32 v98, -v97, v96, v201
	v_cmp_ge_f32_e64 s[0:1], 0, v98
	v_add_u32_e32 v98, 1, v96
	s_nop 0
	v_cndmask_b32_e64 v97, v96, v97, s[0:1]
	v_fma_f32 v96, -v98, v96, v201
	v_cmp_lt_f32_e64 s[0:1], 0, v96
	s_nop 1
	v_cndmask_b32_e64 v96, v97, v98, s[0:1]
	v_mul_f32_e32 v97, 0x37800000, v96
	v_cndmask_b32_e32 v96, v96, v97, vcc
	v_cmp_class_f32_e32 vcc, v201, v217
	s_nop 1
	v_cndmask_b32_e32 v201, v96, v201, vcc
	v_div_scale_f32 v96, s[0:1], v201, v201, 1.0
	v_rcp_f32_e32 v97, v96
	s_nop 0
	v_fma_f32 v98, -v96, v97, 1.0
	v_fmac_f32_e32 v97, v98, v97
	v_div_scale_f32 v98, vcc, 1.0, v201, 1.0
	v_mul_f32_e32 v99, v98, v97
	v_fma_f32 v100, -v96, v99, v98
	v_fmac_f32_e32 v99, v100, v97
	v_fma_f32 v96, -v96, v99, v98
	v_div_fmas_f32 v96, v96, v97, v99
	v_div_fixup_f32 v201, v96, v201, 1.0
	v_mul_f32_e32 v164, v164, v201
	v_mul_f32_e32 v165, v165, v201
	v_mul_f32_e32 v166, v166, v201
	v_mul_f32_e32 v167, v167, v201
	v_mul_f32_e32 v96, v2, v164
	v_cvt_pk_bf16_f32 v96, v96, s0
	v_mul_f32_e32 v97, v3, v165
	v_cvt_pk_bf16_f32 v97, v97, s0
	v_mul_f32_e32 v98, v4, v166
	v_cvt_pk_bf16_f32 v98, v98, s0
	v_mul_f32_e32 v99, v5, v167
	v_cvt_pk_bf16_f32 v99, v99, s0
	ds_write_b16 v19, v96 offset:18
	ds_write_b16 v19, v97 offset:290
	ds_write_b16 v19, v98 offset:562
	ds_write_b16 v19, v99 offset:834
	v_fmamk_f32 v202, v202, 0x3b800000, v216
	v_cmp_gt_f32_e32 vcc, s69, v202
	v_mul_f32_e32 v96, 0x4f800000, v202
	s_nop 0
	v_cndmask_b32_e32 v202, v202, v96, vcc
	v_sqrt_f32_e32 v96, v202
	s_nop 0
	v_add_u32_e32 v97, -1, v96
	v_fma_f32 v98, -v97, v96, v202
	v_cmp_ge_f32_e64 s[0:1], 0, v98
	v_add_u32_e32 v98, 1, v96
	s_nop 0
	v_cndmask_b32_e64 v97, v96, v97, s[0:1]
	v_fma_f32 v96, -v98, v96, v202
	v_cmp_lt_f32_e64 s[0:1], 0, v96
	s_nop 1
	v_cndmask_b32_e64 v96, v97, v98, s[0:1]
	v_mul_f32_e32 v97, 0x37800000, v96
	v_cndmask_b32_e32 v96, v96, v97, vcc
	v_cmp_class_f32_e32 vcc, v202, v217
	s_nop 1
	v_cndmask_b32_e32 v202, v96, v202, vcc
	v_div_scale_f32 v96, s[0:1], v202, v202, 1.0
	v_rcp_f32_e32 v97, v96
	s_nop 0
	v_fma_f32 v98, -v96, v97, 1.0
	v_fmac_f32_e32 v97, v98, v97
	v_div_scale_f32 v98, vcc, 1.0, v202, 1.0
	v_mul_f32_e32 v99, v98, v97
	v_fma_f32 v100, -v96, v99, v98
	v_fmac_f32_e32 v99, v100, v97
	v_fma_f32 v96, -v96, v99, v98
	v_div_fmas_f32 v96, v96, v97, v99
	v_div_fixup_f32 v202, v96, v202, 1.0
	v_mul_f32_e32 v168, v168, v202
	v_mul_f32_e32 v169, v169, v202
	v_mul_f32_e32 v170, v170, v202
	v_mul_f32_e32 v171, v171, v202
	v_mul_f32_e32 v96, v2, v168
	v_cvt_pk_bf16_f32 v96, v96, s0
	v_mul_f32_e32 v97, v3, v169
	v_cvt_pk_bf16_f32 v97, v97, s0
	v_mul_f32_e32 v98, v4, v170
	v_cvt_pk_bf16_f32 v98, v98, s0
	v_mul_f32_e32 v99, v5, v171
	v_cvt_pk_bf16_f32 v99, v99, s0
	ds_write_b16 v19, v96 offset:20
	ds_write_b16 v19, v97 offset:292
	ds_write_b16 v19, v98 offset:564
	ds_write_b16 v19, v99 offset:836
	v_fmamk_f32 v203, v203, 0x3b800000, v216
	v_cmp_gt_f32_e32 vcc, s69, v203
	v_mul_f32_e32 v96, 0x4f800000, v203
	s_nop 0
	v_cndmask_b32_e32 v203, v203, v96, vcc
	v_sqrt_f32_e32 v96, v203
	s_nop 0
	v_add_u32_e32 v97, -1, v96
	v_fma_f32 v98, -v97, v96, v203
	v_cmp_ge_f32_e64 s[0:1], 0, v98
	v_add_u32_e32 v98, 1, v96
	s_nop 0
	v_cndmask_b32_e64 v97, v96, v97, s[0:1]
	v_fma_f32 v96, -v98, v96, v203
	v_cmp_lt_f32_e64 s[0:1], 0, v96
	s_nop 1
	v_cndmask_b32_e64 v96, v97, v98, s[0:1]
	v_mul_f32_e32 v97, 0x37800000, v96
	v_cndmask_b32_e32 v96, v96, v97, vcc
	v_cmp_class_f32_e32 vcc, v203, v217
	s_nop 1
	v_cndmask_b32_e32 v203, v96, v203, vcc
	v_div_scale_f32 v96, s[0:1], v203, v203, 1.0
	v_rcp_f32_e32 v97, v96
	s_nop 0
	v_fma_f32 v98, -v96, v97, 1.0
	v_fmac_f32_e32 v97, v98, v97
	v_div_scale_f32 v98, vcc, 1.0, v203, 1.0
	v_mul_f32_e32 v99, v98, v97
	v_fma_f32 v100, -v96, v99, v98
	v_fmac_f32_e32 v99, v100, v97
	v_fma_f32 v96, -v96, v99, v98
	v_div_fmas_f32 v96, v96, v97, v99
	v_div_fixup_f32 v203, v96, v203, 1.0
	v_mul_f32_e32 v172, v172, v203
	v_mul_f32_e32 v173, v173, v203
	v_mul_f32_e32 v174, v174, v203
	v_mul_f32_e32 v175, v175, v203
	v_mul_f32_e32 v96, v2, v172
	v_cvt_pk_bf16_f32 v96, v96, s0
	v_mul_f32_e32 v97, v3, v173
	v_cvt_pk_bf16_f32 v97, v97, s0
	v_mul_f32_e32 v98, v4, v174
	v_cvt_pk_bf16_f32 v98, v98, s0
	v_mul_f32_e32 v99, v5, v175
	v_cvt_pk_bf16_f32 v99, v99, s0
	ds_write_b16 v19, v96 offset:22
	ds_write_b16 v19, v97 offset:294
	ds_write_b16 v19, v98 offset:566
	ds_write_b16 v19, v99 offset:838
	v_fmamk_f32 v204, v204, 0x3b800000, v216
	v_cmp_gt_f32_e32 vcc, s69, v204
	v_mul_f32_e32 v96, 0x4f800000, v204
	s_nop 0
	v_cndmask_b32_e32 v204, v204, v96, vcc
	v_sqrt_f32_e32 v96, v204
	s_nop 0
	v_add_u32_e32 v97, -1, v96
	v_fma_f32 v98, -v97, v96, v204
	v_cmp_ge_f32_e64 s[0:1], 0, v98
	v_add_u32_e32 v98, 1, v96
	s_nop 0
	v_cndmask_b32_e64 v97, v96, v97, s[0:1]
	v_fma_f32 v96, -v98, v96, v204
	v_cmp_lt_f32_e64 s[0:1], 0, v96
	s_nop 1
	v_cndmask_b32_e64 v96, v97, v98, s[0:1]
; __device__ __forceinline__ unsigned cvtpk_s(float lo, float hi) { typedef __bf16 bf16x2_t __attribute__((ext_vector_type(2))); f32x2 v = {lo, hi}; bf16x2_t b = __builtin_convertvector(v, bf16x2_t); return __builtin_bit_cast(unsigned, b); }
; __device__ __forceinline__ void sg_unit(const Params& P, int l, int chunk, char* shm, float* ssb) {
;     ...
;         const float rstd = 1.f / sqrtf(wave_sum((sq[0] + sq[1]) + (sq[2] + sq[3])) * (1.f / 256.f) + LN_EPS);
;         v = v * rstd * g4;
; #pragma unroll
;         for (int j = 0; j < 4; ++j) vt[(4 * lane + j) * SG_VT_PITCH + q] = (bf16_t)(at::cvtpk_s(v[j], 0.f) & 0xffffu);
;     }
;     asm volatile("s_waitcnt lgkmcnt(0)\n\ts_barrier" ::: "memory");
;     const int g = wid >> 1, ph = wid & 1, r32 = lane & 31, hi = lane >> 5;
	v_mul_f32_e32 v97, 0x37800000, v96
	v_cndmask_b32_e32 v96, v96, v97, vcc
	v_cmp_class_f32_e32 vcc, v204, v217
	s_nop 1
	v_cndmask_b32_e32 v204, v96, v204, vcc
	v_div_scale_f32 v96, s[0:1], v204, v204, 1.0
	v_rcp_f32_e32 v97, v96
	s_nop 0
	v_fma_f32 v98, -v96, v97, 1.0
	v_fmac_f32_e32 v97, v98, v97
	v_div_scale_f32 v98, vcc, 1.0, v204, 1.0
	v_mul_f32_e32 v99, v98, v97
	v_fma_f32 v100, -v96, v99, v98
	v_fmac_f32_e32 v99, v100, v97
	v_fma_f32 v96, -v96, v99, v98
	v_div_fmas_f32 v96, v96, v97, v99
	v_div_fixup_f32 v204, v96, v204, 1.0
	v_mul_f32_e32 v176, v176, v204
	v_mul_f32_e32 v177, v177, v204
	v_mul_f32_e32 v178, v178, v204
	v_mul_f32_e32 v179, v179, v204
	v_mul_f32_e32 v96, v2, v176
	v_cvt_pk_bf16_f32 v96, v96, s0
	v_mul_f32_e32 v97, v3, v177
	v_cvt_pk_bf16_f32 v97, v97, s0
	v_mul_f32_e32 v98, v4, v178
	v_cvt_pk_bf16_f32 v98, v98, s0
	v_mul_f32_e32 v99, v5, v179
	v_cvt_pk_bf16_f32 v99, v99, s0
	ds_write_b16 v19, v96 offset:24
	ds_write_b16 v19, v97 offset:296
	ds_write_b16 v19, v98 offset:568
	ds_write_b16 v19, v99 offset:840
	v_fmamk_f32 v205, v205, 0x3b800000, v216
	v_cmp_gt_f32_e32 vcc, s69, v205
	v_mul_f32_e32 v96, 0x4f800000, v205
	s_nop 0
	v_cndmask_b32_e32 v205, v205, v96, vcc
	v_sqrt_f32_e32 v96, v205
	s_nop 0
	v_add_u32_e32 v97, -1, v96
	v_fma_f32 v98, -v97, v96, v205
	v_cmp_ge_f32_e64 s[0:1], 0, v98
	v_add_u32_e32 v98, 1, v96
	s_nop 0
	v_cndmask_b32_e64 v97, v96, v97, s[0:1]
	v_fma_f32 v96, -v98, v96, v205
	v_cmp_lt_f32_e64 s[0:1], 0, v96
	s_nop 1
	v_cndmask_b32_e64 v96, v97, v98, s[0:1]
	v_mul_f32_e32 v97, 0x37800000, v96
	v_cndmask_b32_e32 v96, v96, v97, vcc
	v_cmp_class_f32_e32 vcc, v205, v217
	s_nop 1
	v_cndmask_b32_e32 v205, v96, v205, vcc
	v_div_scale_f32 v96, s[0:1], v205, v205, 1.0
	v_rcp_f32_e32 v97, v96
	s_nop 0
	v_fma_f32 v98, -v96, v97, 1.0
	v_fmac_f32_e32 v97, v98, v97
	v_div_scale_f32 v98, vcc, 1.0, v205, 1.0
	v_mul_f32_e32 v99, v98, v97
	v_fma_f32 v100, -v96, v99, v98
	v_fmac_f32_e32 v99, v100, v97
	v_fma_f32 v96, -v96, v99, v98
	v_div_fmas_f32 v96, v96, v97, v99
	v_div_fixup_f32 v205, v96, v205, 1.0
	v_mul_f32_e32 v180, v180, v205
	v_mul_f32_e32 v181, v181, v205
	v_mul_f32_e32 v182, v182, v205
	v_mul_f32_e32 v183, v183, v205
	v_mul_f32_e32 v96, v2, v180
	v_cvt_pk_bf16_f32 v96, v96, s0
	v_mul_f32_e32 v97, v3, v181
	v_cvt_pk_bf16_f32 v97, v97, s0
	v_mul_f32_e32 v98, v4, v182
	v_cvt_pk_bf16_f32 v98, v98, s0
	v_mul_f32_e32 v99, v5, v183
	v_cvt_pk_bf16_f32 v99, v99, s0
	ds_write_b16 v19, v96 offset:26
	ds_write_b16 v19, v97 offset:298
	ds_write_b16 v19, v98 offset:570
	ds_write_b16 v19, v99 offset:842
	v_fmamk_f32 v206, v206, 0x3b800000, v216
	v_cmp_gt_f32_e32 vcc, s69, v206
	v_mul_f32_e32 v96, 0x4f800000, v206
	s_nop 0
	v_cndmask_b32_e32 v206, v206, v96, vcc
	v_sqrt_f32_e32 v96, v206
	s_nop 0
	v_add_u32_e32 v97, -1, v96
	v_fma_f32 v98, -v97, v96, v206
	v_cmp_ge_f32_e64 s[0:1], 0, v98
	v_add_u32_e32 v98, 1, v96
	s_nop 0
	v_cndmask_b32_e64 v97, v96, v97, s[0:1]
	v_fma_f32 v96, -v98, v96, v206
	v_cmp_lt_f32_e64 s[0:1], 0, v96
	s_nop 1
	v_cndmask_b32_e64 v96, v97, v98, s[0:1]
	v_mul_f32_e32 v97, 0x37800000, v96
	v_cndmask_b32_e32 v96, v96, v97, vcc
	v_cmp_class_f32_e32 vcc, v206, v217
	s_nop 1
	v_cndmask_b32_e32 v206, v96, v206, vcc
	v_div_scale_f32 v96, s[0:1], v206, v206, 1.0
	v_rcp_f32_e32 v97, v96
	s_nop 0
	v_fma_f32 v98, -v96, v97, 1.0
	v_fmac_f32_e32 v97, v98, v97
	v_div_scale_f32 v98, vcc, 1.0, v206, 1.0
	v_mul_f32_e32 v99, v98, v97
	v_fma_f32 v100, -v96, v99, v98
	v_fmac_f32_e32 v99, v100, v97
	v_fma_f32 v96, -v96, v99, v98
	v_div_fmas_f32 v96, v96, v97, v99
	v_div_fixup_f32 v206, v96, v206, 1.0
	v_mul_f32_e32 v184, v184, v206
	v_mul_f32_e32 v185, v185, v206
	v_mul_f32_e32 v186, v186, v206
	v_mul_f32_e32 v187, v187, v206
	v_mul_f32_e32 v96, v2, v184
	v_cvt_pk_bf16_f32 v96, v96, s0
	v_mul_f32_e32 v97, v3, v185
	v_cvt_pk_bf16_f32 v97, v97, s0
	v_mul_f32_e32 v98, v4, v186
	v_cvt_pk_bf16_f32 v98, v98, s0
	v_mul_f32_e32 v99, v5, v187
	v_cvt_pk_bf16_f32 v99, v99, s0
	ds_write_b16 v19, v96 offset:28
	ds_write_b16 v19, v97 offset:300
	ds_write_b16 v19, v98 offset:572
	ds_write_b16 v19, v99 offset:844
	v_fmamk_f32 v207, v207, 0x3b800000, v216
	v_cmp_gt_f32_e32 vcc, s69, v207
	v_mul_f32_e32 v96, 0x4f800000, v207
	s_nop 0
	v_cndmask_b32_e32 v207, v207, v96, vcc
	v_sqrt_f32_e32 v96, v207
	s_nop 0
	v_add_u32_e32 v97, -1, v96
	v_fma_f32 v98, -v97, v96, v207
	v_cmp_ge_f32_e64 s[0:1], 0, v98
	v_add_u32_e32 v98, 1, v96
	s_nop 0
	v_cndmask_b32_e64 v97, v96, v97, s[0:1]
	v_fma_f32 v96, -v98, v96, v207
	v_cmp_lt_f32_e64 s[0:1], 0, v96
	s_nop 1
	v_cndmask_b32_e64 v96, v97, v98, s[0:1]
	v_mul_f32_e32 v97, 0x37800000, v96
	v_cndmask_b32_e32 v96, v96, v97, vcc
	v_cmp_class_f32_e32 vcc, v207, v217
	s_nop 1
	v_cndmask_b32_e32 v207, v96, v207, vcc
	v_div_scale_f32 v96, s[0:1], v207, v207, 1.0
	v_rcp_f32_e32 v97, v96
	s_nop 0
	v_fma_f32 v98, -v96, v97, 1.0
	v_fmac_f32_e32 v97, v98, v97
	v_div_scale_f32 v98, vcc, 1.0, v207, 1.0
	v_mul_f32_e32 v99, v98, v97
	v_fma_f32 v100, -v96, v99, v98
	v_fmac_f32_e32 v99, v100, v97
	v_fma_f32 v96, -v96, v99, v98
	v_div_fmas_f32 v96, v96, v97, v99
	v_div_fixup_f32 v207, v96, v207, 1.0
	v_mul_f32_e32 v188, v188, v207
	v_mul_f32_e32 v189, v189, v207
	v_mul_f32_e32 v190, v190, v207
	v_mul_f32_e32 v191, v191, v207
	v_mul_f32_e32 v96, v2, v188
	v_cvt_pk_bf16_f32 v96, v96, s0
	v_mul_f32_e32 v97, v3, v189
	v_cvt_pk_bf16_f32 v97, v97, s0
	v_mul_f32_e32 v98, v4, v190
	v_cvt_pk_bf16_f32 v98, v98, s0
	v_mul_f32_e32 v99, v5, v191
	v_cvt_pk_bf16_f32 v99, v99, s0
	ds_write_b16 v19, v96 offset:30
	ds_write_b16 v19, v97 offset:302
	ds_write_b16 v19, v98 offset:574
	ds_write_b16 v19, v99 offset:846
	s_lshl_b32 s7, s3, 7
	s_add_u32 s10, s4, 0x200000
	s_addc_u32 s11, s5, 0
	s_ashr_i32 s4, s6, 7
	s_ashr_i32 s5, s4, 31
	s_bfe_u32 s1, s6, 0x10006
	s_lshl_b64 s[8:9], s[4:5], 15
	v_readlane_b32 s0, v252, 20
	v_and_b32_e32 v14, 31, v12
	v_lshrrev_b32_e32 v15, 5, v13
	s_add_u32 s8, s0, s8
	v_readlane_b32 s0, v252, 21
	s_addc_u32 s9, s0, s9
	v_lshlrev_b32_e32 v0, 4, v15
	v_lshlrev_b32_e32 v2, 8, v14
	v_lshl_add_u64 v[4:5], s[8:9], 0, v[0:1]
	v_lshl_or_b32 v10, s1, 14, v2
	v_mov_b32_e32 v11, v1
	s_waitcnt lgkmcnt(0)
	s_barrier
; __device__ __forceinline__ float bf2f(unsigned short h) { return __uint_as_float(((unsigned)h) << 16); }
; __device__ __forceinline__ int crow(int r, int hi) { return (r & 3) + 8 * (r >> 2) + 4 * hi; }
; __device__ __forceinline__ void sg_unit(const Params& P, int l, int chunk, char* shm, float* ssb) {
;     ...
;     const bf16_t* Wg = Wsb + (size_t)g * 128 * 128;
; #pragma unroll
;     for (int k0 = 0; k0 < 128; k0 += 16) {
;         bf16x8 af[2], bfr[2];
; #pragma unroll
;         for (int pt = 0; pt < 2; ++pt) af[pt] = *(const bf16x8*)(Wg + (size_t)(64 * ph + 32 * pt + r32) * 128 + k0 + 8 * hi);
; #pragma unroll
;         for (int ct = 0; ct < 2; ++ct) bfr[ct] = *(const bf16x8*)(vt + (64 * g + 32 * ct + r32) * SG_VT_PITCH + k0 + 8 * hi);
; #pragma unroll
;         for (int pt = 0; pt < 2; ++pt)
; #pragma unroll
;             for (int ct = 0; ct < 2; ++ct) acc[pt][ct] = __builtin_amdgcn_mfma_f32_32x32x16_bf16(af[pt], bfr[ct], acc[pt][ct], 0, 0, 0);
;     }
;     const float* bs = P.b_s + (size_t)l * 512 + g * 128;
;     float ones[16];
; #pragma unroll
;     for (int r = 0; r < 16; ++r) ones[r] = 1.0f;
; #pragma unroll
;     for (int pt = 0; pt < 2; ++pt) {
;         f32x16 o[2];
; #pragma unroll
;         for (int r = 0; r < 16; ++r) { const int p = 64 * ph + 32 * pt + at::crow(r, hi); const float bp = bs[p];
; #pragma unroll
;             for (int ct = 0; ct < 2; ++ct) { const float uu = bf2f(qkv[(size_t)(R0 + p) * DIN + C_U + 64 * g + 32 * ct + r32]); o[ct][r] = uu * (acc[pt][ct][r] + bp); } }
	v_lshl_add_u64 v[2:3], v[4:5], 0, v[10:11]
	global_load_dwordx4 v[6:9], v[2:3], off
	v_or_b32_e32 v10, 0x2000, v10
	v_lshl_add_u64 v[4:5], v[4:5], 0, v[10:11]
	global_load_dwordx4 v[18:21], v[4:5], off
	s_lshl_b32 s0, s4, 6
	v_or_b32_e32 v22, s0, v14
	s_movk_i32 s4, 0x110
	v_mul_lo_u32 v10, v22, s4
	v_add3_u32 v0, 0, v0, v10
	ds_read_b128 v[22:25], v0 offset:8704
	ds_read_b128 v[26:29], v0
	ds_read_b128 v[84:87], v0 offset:32
	s_and_b32 s4, s6, 0xffffff80
	s_ashr_i32 s5, s4, 31
	s_lshl_b64 s[4:5], s[4:5], 2
	v_readlane_b32 s6, v252, 22
	s_add_u32 s4, s6, s4
	v_readlane_b32 s6, v252, 23
	s_addc_u32 s5, s6, s5
	s_lshl_b32 s6, s1, 6
	s_or_b32 s86, s6, s7
	s_ashr_i32 s1, s0, 31
	s_lshl_b32 s2, s2, 12
	s_add_i32 s2, s2, 0
	s_lshl_b64 s[0:1], s[0:1], 1
	s_add_i32 s2, s2, 0x12000
	v_lshlrev_b32_e32 v10, 1, v14
	s_waitcnt vmcnt(1) lgkmcnt(1)
	v_mfma_f32_32x32x16_bf16 v[66:81], v[6:9], v[26:29], 0
	v_mfma_f32_32x32x16_bf16 v[50:65], v[6:9], v[22:25], 0
	global_load_dwordx4 v[6:9], v[2:3], off offset:32
	global_load_dwordx4 v[88:91], v[4:5], off offset:32
	ds_read_b128 v[92:95], v0 offset:8736
	s_waitcnt vmcnt(2)
	v_mfma_f32_32x32x16_bf16 v[34:49], v[18:21], v[26:29], 0
	v_mfma_f32_32x32x16_bf16 v[18:33], v[18:21], v[22:25], 0
	s_waitcnt vmcnt(1) lgkmcnt(1)
	v_mfma_f32_32x32x16_bf16 v[66:81], v[6:9], v[84:87], v[66:81]
	s_waitcnt lgkmcnt(0)
	v_mfma_f32_32x32x16_bf16 v[50:65], v[6:9], v[92:95], v[50:65]
	s_waitcnt vmcnt(0)
	v_mfma_f32_32x32x16_bf16 v[34:49], v[88:91], v[84:87], v[34:49]
	global_load_dwordx4 v[6:9], v[2:3], off offset:64
	global_load_dwordx4 v[84:87], v[4:5], off offset:64
	v_mfma_f32_32x32x16_bf16 v[18:33], v[88:91], v[92:95], v[18:33]
	ds_read_b128 v[88:91], v0 offset:64
	ds_read_b128 v[92:95], v0 offset:8768
	s_waitcnt vmcnt(1) lgkmcnt(1)
	v_mfma_f32_32x32x16_bf16 v[66:81], v[6:9], v[88:91], v[66:81]
	s_waitcnt lgkmcnt(0)
	v_mfma_f32_32x32x16_bf16 v[50:65], v[6:9], v[92:95], v[50:65]
	s_waitcnt vmcnt(0)
	v_mfma_f32_32x32x16_bf16 v[34:49], v[84:87], v[88:91], v[34:49]
	v_mfma_f32_32x32x16_bf16 v[18:33], v[84:87], v[92:95], v[18:33]
	global_load_dwordx4 v[6:9], v[2:3], off offset:96
	global_load_dwordx4 v[84:87], v[4:5], off offset:96
	ds_read_b128 v[88:91], v0 offset:96
	ds_read_b128 v[92:95], v0 offset:8800
	s_waitcnt vmcnt(1) lgkmcnt(1)
	v_mfma_f32_32x32x16_bf16 v[66:81], v[6:9], v[88:91], v[66:81]
	s_waitcnt lgkmcnt(0)
	v_mfma_f32_32x32x16_bf16 v[50:65], v[6:9], v[92:95], v[50:65]
	s_waitcnt vmcnt(0)
	v_mfma_f32_32x32x16_bf16 v[34:49], v[84:87], v[88:91], v[34:49]
	v_mfma_f32_32x32x16_bf16 v[18:33], v[84:87], v[92:95], v[18:33]
	global_load_dwordx4 v[6:9], v[2:3], off offset:128
	global_load_dwordx4 v[84:87], v[4:5], off offset:128
	ds_read_b128 v[88:91], v0 offset:128
	ds_read_b128 v[92:95], v0 offset:8832
	s_waitcnt vmcnt(1) lgkmcnt(1)
	v_mfma_f32_32x32x16_bf16 v[66:81], v[6:9], v[88:91], v[66:81]
	s_waitcnt lgkmcnt(0)
	v_mfma_f32_32x32x16_bf16 v[50:65], v[6:9], v[92:95], v[50:65]
	s_waitcnt vmcnt(0)
	v_mfma_f32_32x32x16_bf16 v[34:49], v[84:87], v[88:91], v[34:49]
	v_mfma_f32_32x32x16_bf16 v[18:33], v[84:87], v[92:95], v[18:33]
	global_load_dwordx4 v[6:9], v[2:3], off offset:160
	global_load_dwordx4 v[84:87], v[4:5], off offset:160
	ds_read_b128 v[88:91], v0 offset:160
	ds_read_b128 v[92:95], v0 offset:8864
	s_waitcnt vmcnt(1) lgkmcnt(1)
	v_mfma_f32_32x32x16_bf16 v[66:81], v[6:9], v[88:91], v[66:81]
	s_waitcnt lgkmcnt(0)
	v_mfma_f32_32x32x16_bf16 v[50:65], v[6:9], v[92:95], v[50:65]
	s_waitcnt vmcnt(0)
	v_mfma_f32_32x32x16_bf16 v[34:49], v[84:87], v[88:91], v[34:49]
	v_mfma_f32_32x32x16_bf16 v[18:33], v[84:87], v[92:95], v[18:33]
	global_load_dwordx4 v[6:9], v[2:3], off offset:192
	global_load_dwordx4 v[84:87], v[4:5], off offset:192
	ds_read_b128 v[88:91], v0 offset:192
	ds_read_b128 v[92:95], v0 offset:8896
	s_waitcnt vmcnt(1) lgkmcnt(1)
	v_mfma_f32_32x32x16_bf16 v[66:81], v[6:9], v[88:91], v[66:81]
	s_waitcnt lgkmcnt(0)
	v_mfma_f32_32x32x16_bf16 v[50:65], v[6:9], v[92:95], v[50:65]
	global_load_dwordx4 v[6:9], v[2:3], off offset:224
	s_nop 0
	global_load_dwordx4 v[2:5], v[4:5], off offset:224
	s_waitcnt vmcnt(2)
	v_mfma_f32_32x32x16_bf16 v[34:49], v[84:87], v[88:91], v[34:49]
	v_mfma_f32_32x32x16_bf16 v[18:33], v[84:87], v[92:95], v[18:33]
	ds_read_b128 v[84:87], v0 offset:224
	ds_read_b128 v[88:91], v0 offset:8928
	v_lshl_or_b32 v0, v15, 2, s6
	s_waitcnt vmcnt(1) lgkmcnt(1)
	v_mfma_f32_32x32x16_bf16 v[66:81], v[6:9], v[84:87], v[66:81]
	s_waitcnt vmcnt(0)
	v_mfma_f32_32x32x16_bf16 v[34:49], v[2:5], v[84:87], v[34:49]
	v_or_b32_e32 v86, s7, v0
	v_readlane_b32 s6, v254, 8
	v_and_b32_e32 v87, 7, v12
	v_lshlrev_b32_e32 v12, 2, v0
	v_mul_lo_u32 v0, v86, s80
	v_readlane_b32 s7, v254, 9
	v_lshlrev_b32_e32 v14, 4, v87
	s_waitcnt lgkmcnt(0)
	v_mfma_f32_32x32x16_bf16 v[50:65], v[6:9], v[88:91], v[50:65]
	v_mov_b32_e32 v9, v1
	v_cmp_eq_u32_e32 vcc, 0, v87
	v_mov_b32_e32 v7, v1
	v_mfma_f32_32x32x16_bf16 v[18:33], v[2:5], v[88:91], v[18:33]
	v_lshl_add_u64 v[90:91], s[6:7], 0, v[0:1]
	v_lshlrev_b32_e32 v2, 9, v15
	v_lshrrev_b32_e32 v89, 3, v13
	v_lshl_add_u64 v[90:91], v[90:91], 0, s[0:1]
	v_add3_u32 v85, s2, v2, v10
	v_add_u32_e32 v88, s2, v14
	v_lshlrev_b32_e32 v2, 7, v89
	v_lshl_add_u64 v[90:91], v[90:91], 0, v[10:11]
	v_add_u32_e32 v84, v88, v2
	global_load_dwordx4 v[2:5], v12, s[4:5]
	global_load_ushort v0, v[90:91], off offset:1024
	v_lshlrev_b32_e32 v8, 11, v89
	v_lshlrev_b32_e32 v6, 4, v89
	s_waitcnt vmcnt(1)
	v_add_f32_e32 v13, v66, v2
	s_waitcnt vmcnt(0)
	v_lshlrev_b32_e32 v0, 16, v0
	v_mul_f32_e32 v13, v13, v0
	global_load_ushort v0, v[90:91], off offset:1088
	v_add_f32_e32 v2, v50, v2
	v_add_f32_e32 v66, v68, v4
	s_waitcnt vmcnt(0)
; __device__ __forceinline__ float bf2f(unsigned short h) { return __uint_as_float(((unsigned)h) << 16); }
; __device__ __forceinline__ int crow(int r, int hi) { return (r & 3) + 8 * (r >> 2) + 4 * hi; }
; __device__ __forceinline__ void sg_unit(const Params& P, int l, int chunk, char* shm, float* ssb) {
;     ...
;         for (int r = 0; r < 16; ++r) { const int p = 64 * ph + 32 * pt + at::crow(r, hi); const float bp = bs[p];
; #pragma unroll
;             for (int ct = 0; ct < 2; ++ct) { const float uu = bf2f(qkv[(size_t)(R0 + p) * DIN + C_U + 64 * g + 32 * ct + r32]); o[ct][r] = uu * (acc[pt][ct][r] + bp); } }
	v_lshlrev_b32_e32 v0, 16, v0
	v_mul_f32_e32 v15, v2, v0
	v_or_b32_e32 v0, 1, v86
	v_mul_lo_u32 v0, v0, s80
	v_lshl_add_u64 v[90:91], s[6:7], 0, v[0:1]
	v_lshl_add_u64 v[90:91], v[90:91], 0, s[0:1]
	v_lshl_add_u64 v[90:91], v[90:91], 0, v[10:11]
	global_load_ushort v0, v[90:91], off offset:1024
	v_add_f32_e32 v2, v67, v3
	s_waitcnt vmcnt(0)
	v_lshlrev_b32_e32 v0, 16, v0
	v_mul_f32_e32 v50, v2, v0
	global_load_ushort v0, v[90:91], off offset:1088
	v_add_f32_e32 v2, v51, v3
	s_waitcnt vmcnt(0)
	v_lshlrev_b32_e32 v0, 16, v0
	v_mul_f32_e32 v51, v2, v0
	v_or_b32_e32 v0, 2, v86
	v_mul_lo_u32 v0, v0, s80
	v_lshl_add_u64 v[2:3], s[6:7], 0, v[0:1]
	v_lshl_add_u64 v[2:3], v[2:3], 0, s[0:1]
	v_lshl_add_u64 v[2:3], v[2:3], 0, v[10:11]
	global_load_ushort v0, v[2:3], off offset:1024
	s_waitcnt vmcnt(0)
	v_lshlrev_b32_e32 v0, 16, v0
	v_mul_f32_e32 v66, v66, v0
	global_load_ushort v0, v[2:3], off offset:1088
	v_add_f32_e32 v2, v52, v4
	v_add_f32_e32 v4, v69, v5
	s_waitcnt vmcnt(0)
	v_lshlrev_b32_e32 v0, 16, v0
	v_mul_f32_e32 v52, v2, v0
	v_or_b32_e32 v0, 3, v86
	v_mul_lo_u32 v0, v0, s80
	v_lshl_add_u64 v[2:3], s[6:7], 0, v[0:1]
	v_lshl_add_u64 v[2:3], v[2:3], 0, s[0:1]
	v_lshl_add_u64 v[2:3], v[2:3], 0, v[10:11]
	global_load_ushort v0, v[2:3], off offset:1024
	s_waitcnt vmcnt(0)
	v_lshlrev_b32_e32 v0, 16, v0
	v_mul_f32_e32 v67, v4, v0
	global_load_ushort v0, v[2:3], off offset:1088
	v_add_f32_e32 v2, v53, v5
	s_waitcnt vmcnt(0)
	v_lshlrev_b32_e32 v0, 16, v0
	v_mul_f32_e32 v53, v2, v0
	v_or_b32_e32 v0, 8, v86
	v_mul_lo_u32 v0, v0, s80
	v_lshl_add_u64 v[68:69], s[6:7], 0, v[0:1]
	v_lshl_add_u64 v[68:69], v[68:69], 0, s[0:1]
	v_lshl_add_u64 v[90:91], v[68:69], 0, v[10:11]
	global_load_dwordx4 v[2:5], v12, s[4:5] offset:32
	global_load_ushort v0, v[90:91], off offset:1024
	s_waitcnt vmcnt(1)
	v_add_f32_e32 v68, v70, v2
	s_waitcnt vmcnt(0)
	v_lshlrev_b32_e32 v0, 16, v0
	v_mul_f32_e32 v68, v68, v0
	global_load_ushort v0, v[90:91], off offset:1088
	v_add_f32_e32 v2, v54, v2
	v_add_f32_e32 v70, v72, v4
	s_waitcnt vmcnt(0)
	v_lshlrev_b32_e32 v0, 16, v0
	v_mul_f32_e32 v54, v2, v0
	v_or_b32_e32 v0, 9, v86
	v_mul_lo_u32 v0, v0, s80
	v_lshl_add_u64 v[90:91], s[6:7], 0, v[0:1]
	v_lshl_add_u64 v[90:91], v[90:91], 0, s[0:1]
	v_lshl_add_u64 v[90:91], v[90:91], 0, v[10:11]
	global_load_ushort v0, v[90:91], off offset:1024
	v_add_f32_e32 v2, v71, v3
	s_waitcnt vmcnt(0)
	v_lshlrev_b32_e32 v0, 16, v0
	v_mul_f32_e32 v69, v2, v0
	global_load_ushort v0, v[90:91], off offset:1088
	v_add_f32_e32 v2, v55, v3
	s_waitcnt vmcnt(0)
	v_lshlrev_b32_e32 v0, 16, v0
	v_mul_f32_e32 v55, v2, v0
	v_or_b32_e32 v0, 10, v86
	v_mul_lo_u32 v0, v0, s80
	v_lshl_add_u64 v[2:3], s[6:7], 0, v[0:1]
	v_lshl_add_u64 v[2:3], v[2:3], 0, s[0:1]
	v_lshl_add_u64 v[2:3], v[2:3], 0, v[10:11]
	global_load_ushort v0, v[2:3], off offset:1024
	s_waitcnt vmcnt(0)
	v_lshlrev_b32_e32 v0, 16, v0
	v_mul_f32_e32 v70, v70, v0
	global_load_ushort v0, v[2:3], off offset:1088
	v_add_f32_e32 v2, v56, v4
	v_add_f32_e32 v4, v73, v5
	s_waitcnt vmcnt(0)
	v_lshlrev_b32_e32 v0, 16, v0
	v_mul_f32_e32 v56, v2, v0
	v_or_b32_e32 v0, 11, v86
	v_mul_lo_u32 v0, v0, s80
	v_lshl_add_u64 v[2:3], s[6:7], 0, v[0:1]
	v_lshl_add_u64 v[2:3], v[2:3], 0, s[0:1]
	v_lshl_add_u64 v[2:3], v[2:3], 0, v[10:11]
	global_load_ushort v0, v[2:3], off offset:1024
	s_waitcnt vmcnt(0)
	v_lshlrev_b32_e32 v0, 16, v0
	v_mul_f32_e32 v71, v4, v0
	global_load_ushort v0, v[2:3], off offset:1088
	v_add_f32_e32 v2, v57, v5
	s_waitcnt vmcnt(0)
	v_lshlrev_b32_e32 v0, 16, v0
	v_mul_f32_e32 v57, v2, v0
	v_or_b32_e32 v0, 16, v86
	v_mul_lo_u32 v0, v0, s80
	v_lshl_add_u64 v[72:73], s[6:7], 0, v[0:1]
	v_lshl_add_u64 v[72:73], v[72:73], 0, s[0:1]
	v_lshl_add_u64 v[90:91], v[72:73], 0, v[10:11]
	global_load_dwordx4 v[2:5], v12, s[4:5] offset:64
	global_load_ushort v0, v[90:91], off offset:1024
	s_waitcnt vmcnt(1)
	v_add_f32_e32 v72, v74, v2
	s_waitcnt vmcnt(0)
	v_lshlrev_b32_e32 v0, 16, v0
	v_mul_f32_e32 v72, v72, v0
	global_load_ushort v0, v[90:91], off offset:1088
	v_add_f32_e32 v2, v58, v2
	v_add_f32_e32 v74, v76, v4
	s_waitcnt vmcnt(0)
	v_lshlrev_b32_e32 v0, 16, v0
	v_mul_f32_e32 v58, v2, v0
	v_or_b32_e32 v0, 17, v86
	v_mul_lo_u32 v0, v0, s80
	v_lshl_add_u64 v[90:91], s[6:7], 0, v[0:1]
	v_lshl_add_u64 v[90:91], v[90:91], 0, s[0:1]
	v_lshl_add_u64 v[90:91], v[90:91], 0, v[10:11]
	global_load_ushort v0, v[90:91], off offset:1024
	v_add_f32_e32 v2, v75, v3
	s_waitcnt vmcnt(0)
	v_lshlrev_b32_e32 v0, 16, v0
	v_mul_f32_e32 v73, v2, v0
	global_load_ushort v0, v[90:91], off offset:1088
	v_add_f32_e32 v2, v59, v3
	s_waitcnt vmcnt(0)
	v_lshlrev_b32_e32 v0, 16, v0
	v_mul_f32_e32 v59, v2, v0
	v_or_b32_e32 v0, 18, v86
	v_mul_lo_u32 v0, v0, s80
	v_lshl_add_u64 v[2:3], s[6:7], 0, v[0:1]
	v_lshl_add_u64 v[2:3], v[2:3], 0, s[0:1]
	v_lshl_add_u64 v[2:3], v[2:3], 0, v[10:11]
	global_load_ushort v0, v[2:3], off offset:1024
	s_waitcnt vmcnt(0)
	v_lshlrev_b32_e32 v0, 16, v0
	v_mul_f32_e32 v74, v74, v0
	global_load_ushort v0, v[2:3], off offset:1088
	v_add_f32_e32 v2, v60, v4
	v_add_f32_e32 v4, v77, v5
	s_waitcnt vmcnt(0)
	v_lshlrev_b32_e32 v0, 16, v0
	v_mul_f32_e32 v60, v2, v0
	v_or_b32_e32 v0, 19, v86
	v_mul_lo_u32 v0, v0, s80
	v_lshl_add_u64 v[2:3], s[6:7], 0, v[0:1]
	v_lshl_add_u64 v[2:3], v[2:3], 0, s[0:1]
	v_lshl_add_u64 v[2:3], v[2:3], 0, v[10:11]
	global_load_ushort v0, v[2:3], off offset:1024
	s_waitcnt vmcnt(0)
	v_lshlrev_b32_e32 v0, 16, v0
	v_mul_f32_e32 v75, v4, v0
	global_load_ushort v0, v[2:3], off offset:1088
	v_add_f32_e32 v2, v61, v5
	s_waitcnt vmcnt(0)
; __device__ __forceinline__ float bf2f(unsigned short h) { return __uint_as_float(((unsigned)h) << 16); }
; __device__ __forceinline__ int crow(int r, int hi) { return (r & 3) + 8 * (r >> 2) + 4 * hi; }
; __device__ __forceinline__ unsigned cvtpk_s(float lo, float hi) { typedef __bf16 bf16x2_t __attribute__((ext_vector_type(2))); f32x2 v = {lo, hi}; bf16x2_t b = __builtin_convertvector(v, bf16x2_t); return __builtin_bit_cast(unsigned, b); }
; __device__ __forceinline__ void store_tile(const f32x16* o, const float* rli, bf16_t* stg, bf16_t* Ow, int pitch, float* ss, int lane, int r32, int hi) {
; #pragma unroll
;     for (int r = 0; r < 16; ++r) { const int orow = crow(r, hi);
; #pragma unroll
;         for (int d0 = 0; d0 < 2; ++d0) stg[orow * 64 + d0 * 32 + r32] = (bf16_t)(cvtpk_s(o[d0][r] * rli[r], 0.f) & 0xffffu); }
;     asm volatile("s_waitcnt lgkmcnt(0)" ::: "memory");
; #pragma unroll
;     for (int i = 0; i < 4; ++i) { const int row = i * 8 + (lane >> 3), ch = lane & 7; const u32x4 v = *(const u32x4*)(stg + row * 64 + ch * 8);
;         { const bf16_t* gp_ = Ow + (long)row * pitch + ch * 8; asm volatile("global_store_dwordx4 %0, %1, off sc0 sc1\n\ts_nop 1" :: "v"(gp_), "v"(v) : "memory"); }
;         float s = 0.f;
; #pragma unroll
;         for (int j = 0; j < 4; ++j) { const float a = __uint_as_float(v[j] << 16), b = __uint_as_float(v[j] & 0xffff0000u); s += a * a + b * b; }
;         s += __shfl_xor(s, 1); s += __shfl_xor(s, 2); s += __shfl_xor(s, 4);
;         if (ch == 0) atomicAdd(ss + (long)row * 4, s); }
; __device__ __forceinline__ void sg_unit(const Params& P, int l, int chunk, char* shm, float* ssb) {
;     ...
;             for (int ct = 0; ct < 2; ++ct) { const float uu = bf2f(qkv[(size_t)(R0 + p) * DIN + C_U + 64 * g + 32 * ct + r32]); o[ct][r] = uu * (acc[pt][ct][r] + bp); } }
;         const int prow = R0 + 64 * ph + 32 * pt;
;         at::store_tile(o, ones, (bf16_t*)(shm + SG_STAGE) + wid * 2048, omix + (size_t)prow * DM + 384 + 64 * g, DM, ssb + (size_t)prow * 4 + 1, lane, r32, hi);
	v_lshlrev_b32_e32 v0, 16, v0
	v_mul_f32_e32 v61, v2, v0
	v_or_b32_e32 v0, 24, v86
	v_mul_lo_u32 v0, v0, s80
	v_lshl_add_u64 v[76:77], s[6:7], 0, v[0:1]
	v_lshl_add_u64 v[76:77], v[76:77], 0, s[0:1]
	v_lshl_add_u64 v[90:91], v[76:77], 0, v[10:11]
	global_load_dwordx4 v[2:5], v12, s[4:5] offset:96
	global_load_ushort v0, v[90:91], off offset:1024
	s_waitcnt vmcnt(1)
	v_add_f32_e32 v76, v78, v2
	s_waitcnt vmcnt(0)
	v_lshlrev_b32_e32 v0, 16, v0
	v_mul_f32_e32 v76, v76, v0
	global_load_ushort v0, v[90:91], off offset:1088
	v_add_f32_e32 v2, v62, v2
	v_add_f32_e32 v62, v79, v3
	v_add_f32_e32 v3, v63, v3
	v_add_f32_e32 v63, v80, v4
	v_add_f32_e32 v4, v64, v4
	s_waitcnt vmcnt(0)
	v_lshlrev_b32_e32 v0, 16, v0
	v_mul_f32_e32 v2, v2, v0
	v_or_b32_e32 v0, 25, v86
	v_mul_lo_u32 v0, v0, s80
	v_lshl_add_u64 v[90:91], s[6:7], 0, v[0:1]
	v_lshl_add_u64 v[90:91], v[90:91], 0, s[0:1]
	v_lshl_add_u64 v[90:91], v[90:91], 0, v[10:11]
	global_load_ushort v0, v[90:91], off offset:1024
	v_cvt_pk_bf16_f32 v2, v2, s0
	ds_write_b16 v85, v2 offset:3136
	s_waitcnt vmcnt(0)
	v_lshlrev_b32_e32 v0, 16, v0
	v_mul_f32_e32 v62, v62, v0
	global_load_ushort v0, v[90:91], off offset:1088
	v_cvt_pk_bf16_f32 v2, v62, s0
	ds_write_b16 v85, v2 offset:3200
	s_waitcnt vmcnt(0)
	v_lshlrev_b32_e32 v0, 16, v0
	v_mul_f32_e32 v3, v3, v0
	v_or_b32_e32 v0, 26, v86
	v_mul_lo_u32 v0, v0, s80
	v_lshl_add_u64 v[78:79], s[6:7], 0, v[0:1]
	v_lshl_add_u64 v[78:79], v[78:79], 0, s[0:1]
	v_lshl_add_u64 v[78:79], v[78:79], 0, v[10:11]
	global_load_ushort v0, v[78:79], off offset:1024
	v_cvt_pk_bf16_f32 v2, v3, s0
	ds_write_b16 v85, v2 offset:3264
	s_waitcnt vmcnt(0)
	v_lshlrev_b32_e32 v0, 16, v0
	v_mul_f32_e32 v63, v63, v0
	global_load_ushort v0, v[78:79], off offset:1088
	v_cvt_pk_bf16_f32 v2, v63, s0
	ds_write_b16 v85, v2 offset:3328
	s_waitcnt vmcnt(0)
	v_lshlrev_b32_e32 v0, 16, v0
	v_mul_f32_e32 v4, v4, v0
	v_or_b32_e32 v0, 27, v86
	v_mul_lo_u32 v0, v0, s80
	v_lshl_add_u64 v[78:79], s[6:7], 0, v[0:1]
	v_lshl_add_u64 v[78:79], v[78:79], 0, s[0:1]
	v_lshl_add_u64 v[78:79], v[78:79], 0, v[10:11]
	global_load_ushort v0, v[78:79], off offset:1024
	v_add_f32_e32 v11, v81, v5
	v_add_f32_e32 v5, v65, v5
	s_lshl_b64 s[6:7], s[86:87], 11
	v_cvt_pk_bf16_f32 v2, v4, s0
	s_add_u32 s2, s76, s6
	ds_write_b16 v85, v2 offset:3392
	s_addc_u32 s6, s77, s7
	s_add_u32 s8, s2, s0
	s_addc_u32 s9, s6, s1
	s_lshl_b64 s[6:7], s[86:87], 4
	s_add_u32 s6, s10, s6
	s_addc_u32 s7, s11, s7
	s_waitcnt vmcnt(0)
	v_lshlrev_b32_e32 v0, 16, v0
	v_mul_f32_e32 v0, v11, v0
	global_load_ushort v11, v[78:79], off offset:1088
	v_cvt_pk_bf16_f32 v0, v0, s0
	ds_write_b16 v85, v0 offset:3456
	s_waitcnt vmcnt(0)
	v_lshlrev_b32_e32 v11, 16, v11
	v_mul_f32_e32 v5, v5, v11
	v_cvt_pk_bf16_f32 v11, v13, s0
	ds_write_b16 v85, v11
	v_cvt_pk_bf16_f32 v11, v15, s0
	ds_write_b16 v85, v11 offset:64
	v_cvt_pk_bf16_f32 v11, v50, s0
	ds_write_b16 v85, v11 offset:128
	v_cvt_pk_bf16_f32 v11, v51, s0
	ds_write_b16 v85, v11 offset:192
	v_cvt_pk_bf16_f32 v11, v66, s0
	ds_write_b16 v85, v11 offset:256
	v_cvt_pk_bf16_f32 v11, v52, s0
	ds_write_b16 v85, v11 offset:320
	v_cvt_pk_bf16_f32 v11, v67, s0
	ds_write_b16 v85, v11 offset:384
	v_cvt_pk_bf16_f32 v11, v53, s0
	ds_write_b16 v85, v11 offset:448
	v_cvt_pk_bf16_f32 v11, v68, s0
	ds_write_b16 v85, v11 offset:1024
	v_cvt_pk_bf16_f32 v11, v54, s0
	ds_write_b16 v85, v11 offset:1088
	v_cvt_pk_bf16_f32 v11, v69, s0
	ds_write_b16 v85, v11 offset:1152
	v_cvt_pk_bf16_f32 v11, v55, s0
	ds_write_b16 v85, v11 offset:1216
	v_cvt_pk_bf16_f32 v11, v70, s0
	ds_write_b16 v85, v11 offset:1280
	v_cvt_pk_bf16_f32 v11, v56, s0
	ds_write_b16 v85, v11 offset:1344
	v_cvt_pk_bf16_f32 v11, v71, s0
	ds_write_b16 v85, v11 offset:1408
	v_cvt_pk_bf16_f32 v11, v57, s0
	ds_write_b16 v85, v11 offset:1472
	v_cvt_pk_bf16_f32 v11, v72, s0
	ds_write_b16 v85, v11 offset:2048
	v_cvt_pk_bf16_f32 v11, v58, s0
	ds_write_b16 v85, v11 offset:2112
	v_cvt_pk_bf16_f32 v11, v73, s0
	ds_write_b16 v85, v11 offset:2176
	v_cvt_pk_bf16_f32 v11, v59, s0
	ds_write_b16 v85, v11 offset:2240
	v_cvt_pk_bf16_f32 v11, v74, s0
	ds_write_b16 v85, v11 offset:2304
	v_cvt_pk_bf16_f32 v11, v60, s0
	ds_write_b16 v85, v11 offset:2368
	v_cvt_pk_bf16_f32 v11, v75, s0
	ds_write_b16 v85, v11 offset:2432
	v_cvt_pk_bf16_f32 v11, v61, s0
	ds_write_b16 v85, v11 offset:2496
	v_cvt_pk_bf16_f32 v11, v76, s0
	v_cvt_pk_bf16_f32 v0, v5, s0
	ds_write_b16 v85, v11 offset:3072
	ds_write_b16 v85, v0 offset:3520
	s_waitcnt lgkmcnt(0)
	ds_read_b128 v[50:53], v84
	v_mov_b32_e32 v15, v1
	v_lshl_add_u64 v[2:3], s[8:9], 0, v[14:15]
	s_mov_b64 s[8:9], 0x12e40300
	v_lshl_add_u64 v[2:3], v[2:3], 0, s[8:9]
	v_lshl_add_u64 v[4:5], v[2:3], 0, v[8:9]
	s_waitcnt lgkmcnt(0)
	global_store_dwordx4 v[4:5], v[50:53], off sc0 sc1
	s_nop 1
	v_and_b32_e32 v4, 0xffff0000, v50
	v_lshlrev_b32_e32 v0, 16, v50
	v_mul_f32_e32 v4, v4, v4
	v_and_b32_e32 v5, 0xffff0000, v51
	v_fmac_f32_e32 v4, v0, v0
	v_lshlrev_b32_e32 v0, 16, v51
	v_mul_f32_e32 v5, v5, v5
	v_fmac_f32_e32 v5, v0, v0
	v_add_f32_e32 v0, v4, v5
	v_and_b32_e32 v5, 0xffff0000, v52
	v_lshlrev_b32_e32 v4, 16, v52
	v_mul_f32_e32 v5, v5, v5
	v_fmac_f32_e32 v5, v4, v4
	v_add_f32_e32 v0, v5, v0
	v_and_b32_e32 v5, 0xffff0000, v53
	v_lshlrev_b32_e32 v4, 16, v53
	v_mul_f32_e32 v5, v5, v5
	v_fmac_f32_e32 v5, v4, v4
	v_add_f32_e32 v0, v5, v0
	ds_bpermute_b32 v4, v17, v0
	s_waitcnt lgkmcnt(0)
	v_add_f32_e32 v0, v0, v4
	ds_bpermute_b32 v4, v83, v0
	s_waitcnt lgkmcnt(0)
	v_add_f32_e32 v0, v0, v4
	ds_bpermute_b32 v4, v82, v0
	s_and_saveexec_b64 s[8:9], vcc
	s_cbranch_execz .LBB0_562
	v_lshl_add_u64 v[14:15], s[6:7], 0, v[6:7]
	s_waitcnt lgkmcnt(0)
	v_add_f32_e32 v0, v0, v4
	flat_atomic_add_f32 v[14:15], v0 offset:4
